# rms fast path + sel-branch wave skip + P45 mid hook loads hoisted
# baseline (speedup 1.0000x reference)
.LBB0_256:
	v_readlane_b32 s0, v249, 1
	v_readlane_b32 s2, v249, 3
	v_readlane_b32 s3, v249, 4
	s_add_u32 s84, s2, 0x3000000
	s_addc_u32 s85, s3, 0
	s_cmpk_gt_i32 s52, 0x7fff
	v_mbcnt_lo_u32_b32 v194, -1, 0
	v_lshlrev_b32_e32 v128, 3, v159
	v_readlane_b32 s1, v249, 2
	s_cbranch_scc1 .LBB0_265
	s_waitcnt lgkmcnt(0)
	v_readlane_b32 s8, v249, 5
	v_mov_b32_e32 v1, 0
	v_readlane_b32 s9, v249, 6
	v_readlane_b32 s10, v249, 7
	v_readlane_b32 s11, v249, 8
	v_lshl_add_u64 v[54:55], s[8:9], 0, v[0:1]
	v_readlane_b32 s14, v249, 11
	v_lshl_add_u64 v[52:53], s[10:11], 0, v[0:1]
	v_mbcnt_hi_u32_b32 v0, -1, v194
	v_and_b32_e32 v2, 64, v0
	v_add_u32_e32 v2, 64, v2
	v_xor_b32_e32 v3, 1, v0
	v_cmp_lt_i32_e32 vcc, v3, v2
	v_readlane_b32 s15, v249, 12
	v_readlane_b32 s16, v249, 13
	v_cndmask_b32_e32 v3, v0, v3, vcc
	v_lshlrev_b32_e32 v58, 2, v3
	v_xor_b32_e32 v3, 2, v0
	v_cmp_lt_i32_e32 vcc, v3, v2
	v_mov_b32_e32 v129, v1
	v_lshl_add_u64 v[56:57], s[84:85], 0, v[128:129]
	v_cndmask_b32_e32 v3, v0, v3, vcc
	v_lshlrev_b32_e32 v59, 2, v3
	v_xor_b32_e32 v3, 4, v0
	v_cmp_lt_i32_e32 vcc, v3, v2
	s_lshl_b32 s14, s86, 5
	s_lshl_b32 s15, s86, 4
	v_cndmask_b32_e32 v3, v0, v3, vcc
	v_lshlrev_b32_e32 v60, 2, v3
	v_xor_b32_e32 v3, 8, v0
	v_cmp_lt_i32_e32 vcc, v3, v2
	s_mul_i32 s16, s86, 24
	v_mov_b32_e32 v64, 0x358637bd
	v_cndmask_b32_e32 v3, v0, v3, vcc
	v_lshlrev_b32_e32 v61, 2, v3
	v_xor_b32_e32 v3, 16, v0
	v_cmp_lt_i32_e32 vcc, v3, v2
	s_mov_b32 s0, s52
	v_readlane_b32 s12, v249, 9
	v_cndmask_b32_e32 v3, v0, v3, vcc
	v_lshlrev_b32_e32 v62, 2, v3
	v_xor_b32_e32 v3, 32, v0
	v_cmp_lt_i32_e32 vcc, v3, v2
	v_readlane_b32 s13, v249, 10
	v_readlane_b32 s17, v249, 14
	v_cndmask_b32_e32 v0, v0, v3, vcc
	v_lshlrev_b32_e32 v63, 2, v0
	v_readlane_b32 s18, v249, 15
	v_readlane_b32 s19, v249, 16
	v_readlane_b32 s20, v249, 17
	v_readlane_b32 s21, v249, 18
	v_readlane_b32 s22, v249, 19
	v_readlane_b32 s23, v249, 20
	s_cmp_lg_u32 s86, 0x100
	s_cbranch_scc1 .LBB0_259
	v_lshlrev_b32_e32 v116, 4, v159
	v_lshlrev_b32_e32 v117, 3, v159
	global_load_dwordx4 v[100:103], v[52:53], off
	global_load_dwordx4 v[104:107], v[52:53], off offset:1024
	global_load_dwordx4 v[108:111], v[52:53], off offset:2048
	global_load_dwordx4 v[112:115], v[52:53], off offset:3072
	s_lshl_b32 s0, s52, 12
	s_add_u32 s4, s8, s0
	s_addc_u32 s5, s9, 0
	s_lshl_b32 s0, s52, 11
	s_add_u32 s20, s84, s0
	s_addc_u32 s21, s85, 0
	s_add_u32 s12, s4, 0x0
	s_addc_u32 s13, s5, 0
	s_add_u32 s14, s4, 0x800000
	s_addc_u32 s15, s5, 0
	global_load_dwordx4 v[0:3], v116, s[12:13] nt
	global_load_dwordx4 v[4:7], v116, s[12:13] offset:1024 nt
	global_load_dwordx4 v[8:11], v116, s[12:13] offset:2048 nt
	global_load_dwordx4 v[12:15], v116, s[12:13] offset:3072 nt
	global_load_dwordx4 v[16:19], v116, s[14:15] nt
	global_load_dwordx4 v[20:23], v116, s[14:15] offset:1024 nt
	global_load_dwordx4 v[24:27], v116, s[14:15] offset:2048 nt
	global_load_dwordx4 v[28:31], v116, s[14:15] offset:3072 nt
	s_add_u32 s12, s4, 0x1000000
	s_addc_u32 s13, s5, 0
	s_add_u32 s14, s4, 0x1800000
	s_addc_u32 s15, s5, 0
	global_load_dwordx4 v[66:69], v116, s[12:13] nt
	global_load_dwordx4 v[70:73], v116, s[12:13] offset:1024 nt
	global_load_dwordx4 v[74:77], v116, s[12:13] offset:2048 nt
	global_load_dwordx4 v[78:81], v116, s[12:13] offset:3072 nt
	global_load_dwordx4 v[82:85], v116, s[14:15] nt
	global_load_dwordx4 v[86:89], v116, s[14:15] offset:1024 nt
	global_load_dwordx4 v[90:93], v116, s[14:15] offset:2048 nt
	global_load_dwordx4 v[94:97], v116, s[14:15] offset:3072 nt
	s_waitcnt vmcnt(8)
	v_pk_mul_f32 v[48:49], v[0:1], v[0:1]
	v_pk_mul_f32 v[50:51], v[16:17], v[16:17]
	v_pk_fma_f32 v[48:49], v[2:3], v[2:3], v[48:49]
	v_pk_fma_f32 v[50:51], v[18:19], v[18:19], v[50:51]
	v_pk_fma_f32 v[48:49], v[4:5], v[4:5], v[48:49]
	v_pk_fma_f32 v[50:51], v[20:21], v[20:21], v[50:51]
	v_pk_fma_f32 v[48:49], v[6:7], v[6:7], v[48:49]
	v_pk_fma_f32 v[50:51], v[22:23], v[22:23], v[50:51]
	v_pk_fma_f32 v[48:49], v[8:9], v[8:9], v[48:49]
	v_pk_fma_f32 v[50:51], v[24:25], v[24:25], v[50:51]
	v_pk_fma_f32 v[48:49], v[10:11], v[10:11], v[48:49]
	v_pk_fma_f32 v[50:51], v[26:27], v[26:27], v[50:51]
	v_pk_fma_f32 v[48:49], v[12:13], v[12:13], v[48:49]
	v_pk_fma_f32 v[50:51], v[28:29], v[28:29], v[50:51]
	v_pk_fma_f32 v[48:49], v[14:15], v[14:15], v[48:49]
	v_pk_fma_f32 v[50:51], v[30:31], v[30:31], v[50:51]
	v_add_f32_e32 v48, v48, v49
	v_add_f32_e32 v50, v50, v51
	ds_bpermute_b32 v49, v58, v48
	ds_bpermute_b32 v51, v58, v50
	s_waitcnt lgkmcnt(0)
	v_add_f32_e32 v48, v48, v49
	v_add_f32_e32 v50, v50, v51
	ds_bpermute_b32 v49, v59, v48
	ds_bpermute_b32 v51, v59, v50
	s_waitcnt lgkmcnt(0)
	v_add_f32_e32 v48, v48, v49
	v_add_f32_e32 v50, v50, v51
	ds_bpermute_b32 v49, v60, v48
	ds_bpermute_b32 v51, v60, v50
	s_waitcnt lgkmcnt(0)
	v_add_f32_e32 v48, v48, v49
	v_add_f32_e32 v50, v50, v51
	ds_bpermute_b32 v49, v61, v48
	ds_bpermute_b32 v51, v61, v50
	s_waitcnt lgkmcnt(0)
	v_add_f32_e32 v48, v48, v49
	v_add_f32_e32 v50, v50, v51
	ds_bpermute_b32 v49, v62, v48
	ds_bpermute_b32 v51, v62, v50
	s_waitcnt lgkmcnt(0)
	v_add_f32_e32 v48, v48, v49
	v_add_f32_e32 v50, v50, v51
	ds_bpermute_b32 v49, v63, v48
	ds_bpermute_b32 v51, v63, v50
	s_waitcnt lgkmcnt(0)
	v_add_f32_e32 v48, v48, v49
	v_add_f32_e32 v50, v50, v51
	v_fmamk_f32 v48, v48, 0x3a800000, v64
	v_fmamk_f32 v50, v50, 0x3a800000, v64
	v_rsq_f32_e32 v48, v48
	v_rsq_f32_e32 v50, v50
	s_nop 0
	v_pk_mul_f32 v[0:1], v[48:49], v[0:1] op_sel_hi:[0,1]
	v_pk_mul_f32 v[2:3], v[48:49], v[2:3] op_sel_hi:[0,1]
	v_pk_mul_f32 v[0:1], v[100:101], v[0:1]
	v_pk_mul_f32 v[2:3], v[102:103], v[2:3]
	v_cvt_pk_bf16_f32 v32, v0, v1
	v_cvt_pk_bf16_f32 v33, v2, v3
	v_pk_mul_f32 v[4:5], v[48:49], v[4:5] op_sel_hi:[0,1]
	v_pk_mul_f32 v[6:7], v[48:49], v[6:7] op_sel_hi:[0,1]
	v_pk_mul_f32 v[4:5], v[104:105], v[4:5]
	v_pk_mul_f32 v[6:7], v[106:107], v[6:7]
	v_cvt_pk_bf16_f32 v34, v4, v5
	v_cvt_pk_bf16_f32 v35, v6, v7
	v_pk_mul_f32 v[8:9], v[48:49], v[8:9] op_sel_hi:[0,1]
	v_pk_mul_f32 v[10:11], v[48:49], v[10:11] op_sel_hi:[0,1]
	v_pk_mul_f32 v[8:9], v[108:109], v[8:9]
	v_pk_mul_f32 v[10:11], v[110:111], v[10:11]
	v_cvt_pk_bf16_f32 v36, v8, v9
	v_cvt_pk_bf16_f32 v37, v10, v11
	v_pk_mul_f32 v[12:13], v[48:49], v[12:13] op_sel_hi:[0,1]
	v_pk_mul_f32 v[14:15], v[48:49], v[14:15] op_sel_hi:[0,1]
	v_pk_mul_f32 v[12:13], v[112:113], v[12:13]
	v_pk_mul_f32 v[14:15], v[114:115], v[14:15]
	v_cvt_pk_bf16_f32 v38, v12, v13
	v_cvt_pk_bf16_f32 v39, v14, v15
	v_pk_mul_f32 v[16:17], v[50:51], v[16:17] op_sel_hi:[0,1]
	v_pk_mul_f32 v[18:19], v[50:51], v[18:19] op_sel_hi:[0,1]
	v_pk_mul_f32 v[16:17], v[100:101], v[16:17]
	v_pk_mul_f32 v[18:19], v[102:103], v[18:19]
	v_cvt_pk_bf16_f32 v40, v16, v17
	v_cvt_pk_bf16_f32 v41, v18, v19
	v_pk_mul_f32 v[20:21], v[50:51], v[20:21] op_sel_hi:[0,1]
	v_pk_mul_f32 v[22:23], v[50:51], v[22:23] op_sel_hi:[0,1]
	v_pk_mul_f32 v[20:21], v[104:105], v[20:21]
	v_pk_mul_f32 v[22:23], v[106:107], v[22:23]
	v_cvt_pk_bf16_f32 v42, v20, v21
	v_cvt_pk_bf16_f32 v43, v22, v23
	v_pk_mul_f32 v[24:25], v[50:51], v[24:25] op_sel_hi:[0,1]
	v_pk_mul_f32 v[26:27], v[50:51], v[26:27] op_sel_hi:[0,1]
	v_pk_mul_f32 v[24:25], v[108:109], v[24:25]
	v_pk_mul_f32 v[26:27], v[110:111], v[26:27]
	v_cvt_pk_bf16_f32 v44, v24, v25
	v_cvt_pk_bf16_f32 v45, v26, v27
	v_pk_mul_f32 v[28:29], v[50:51], v[28:29] op_sel_hi:[0,1]
	v_pk_mul_f32 v[30:31], v[50:51], v[30:31] op_sel_hi:[0,1]
	v_pk_mul_f32 v[28:29], v[112:113], v[28:29]
	v_pk_mul_f32 v[30:31], v[114:115], v[30:31]
	v_cvt_pk_bf16_f32 v46, v28, v29
	v_cvt_pk_bf16_f32 v47, v30, v31
	s_add_u32 s12, s4, 0x2000000
	s_addc_u32 s13, s5, 0
	s_add_u32 s14, s4, 0x2800000
	s_addc_u32 s15, s5, 0
	global_load_dwordx4 v[0:3], v116, s[12:13] nt
	global_load_dwordx4 v[4:7], v116, s[12:13] offset:1024 nt
	global_load_dwordx4 v[8:11], v116, s[12:13] offset:2048 nt
	global_load_dwordx4 v[12:15], v116, s[12:13] offset:3072 nt
	global_load_dwordx4 v[16:19], v116, s[14:15] nt
	global_load_dwordx4 v[20:23], v116, s[14:15] offset:1024 nt
	global_load_dwordx4 v[24:27], v116, s[14:15] offset:2048 nt
	global_load_dwordx4 v[28:31], v116, s[14:15] offset:3072 nt
	s_add_u32 s16, s20, 0x0
	s_addc_u32 s17, s21, 0
	s_add_u32 s18, s20, 0x400000
	s_addc_u32 s19, s21, 0
	global_store_dwordx2 v117, v[32:33], s[16:17]
	global_store_dwordx2 v117, v[34:35], s[16:17] offset:512
	global_store_dwordx2 v117, v[36:37], s[16:17] offset:1024
	global_store_dwordx2 v117, v[38:39], s[16:17] offset:1536
	global_store_dwordx2 v117, v[40:41], s[18:19]
	global_store_dwordx2 v117, v[42:43], s[18:19] offset:512
	global_store_dwordx2 v117, v[44:45], s[18:19] offset:1024
	global_store_dwordx2 v117, v[46:47], s[18:19] offset:1536
	s_waitcnt vmcnt(16)
	v_pk_mul_f32 v[48:49], v[66:67], v[66:67]
	v_pk_mul_f32 v[50:51], v[82:83], v[82:83]
	v_pk_fma_f32 v[48:49], v[68:69], v[68:69], v[48:49]
	v_pk_fma_f32 v[50:51], v[84:85], v[84:85], v[50:51]
	v_pk_fma_f32 v[48:49], v[70:71], v[70:71], v[48:49]
	v_pk_fma_f32 v[50:51], v[86:87], v[86:87], v[50:51]
	v_pk_fma_f32 v[48:49], v[72:73], v[72:73], v[48:49]
	v_pk_fma_f32 v[50:51], v[88:89], v[88:89], v[50:51]
	v_pk_fma_f32 v[48:49], v[74:75], v[74:75], v[48:49]
	v_pk_fma_f32 v[50:51], v[90:91], v[90:91], v[50:51]
	v_pk_fma_f32 v[48:49], v[76:77], v[76:77], v[48:49]
	v_pk_fma_f32 v[50:51], v[92:93], v[92:93], v[50:51]
	v_pk_fma_f32 v[48:49], v[78:79], v[78:79], v[48:49]
	v_pk_fma_f32 v[50:51], v[94:95], v[94:95], v[50:51]
	v_pk_fma_f32 v[48:49], v[80:81], v[80:81], v[48:49]
	v_pk_fma_f32 v[50:51], v[96:97], v[96:97], v[50:51]
	v_add_f32_e32 v48, v48, v49
	v_add_f32_e32 v50, v50, v51
	ds_bpermute_b32 v49, v58, v48
	ds_bpermute_b32 v51, v58, v50
	s_waitcnt lgkmcnt(0)
	v_add_f32_e32 v48, v48, v49
	v_add_f32_e32 v50, v50, v51
	ds_bpermute_b32 v49, v59, v48
	ds_bpermute_b32 v51, v59, v50
	s_waitcnt lgkmcnt(0)
	v_add_f32_e32 v48, v48, v49
	v_add_f32_e32 v50, v50, v51
	ds_bpermute_b32 v49, v60, v48
	ds_bpermute_b32 v51, v60, v50
	s_waitcnt lgkmcnt(0)
	v_add_f32_e32 v48, v48, v49
	v_add_f32_e32 v50, v50, v51
	ds_bpermute_b32 v49, v61, v48
	ds_bpermute_b32 v51, v61, v50
	s_waitcnt lgkmcnt(0)
	v_add_f32_e32 v48, v48, v49
	v_add_f32_e32 v50, v50, v51
	ds_bpermute_b32 v49, v62, v48
	ds_bpermute_b32 v51, v62, v50
	s_waitcnt lgkmcnt(0)
	v_add_f32_e32 v48, v48, v49
	v_add_f32_e32 v50, v50, v51
	ds_bpermute_b32 v49, v63, v48
	ds_bpermute_b32 v51, v63, v50
	s_waitcnt lgkmcnt(0)
	v_add_f32_e32 v48, v48, v49
	v_add_f32_e32 v50, v50, v51
	v_fmamk_f32 v48, v48, 0x3a800000, v64
	v_fmamk_f32 v50, v50, 0x3a800000, v64
	v_rsq_f32_e32 v48, v48
	v_rsq_f32_e32 v50, v50
	s_nop 0
	v_pk_mul_f32 v[66:67], v[48:49], v[66:67] op_sel_hi:[0,1]
	v_pk_mul_f32 v[68:69], v[48:49], v[68:69] op_sel_hi:[0,1]
	v_pk_mul_f32 v[66:67], v[100:101], v[66:67]
	v_pk_mul_f32 v[68:69], v[102:103], v[68:69]
	v_cvt_pk_bf16_f32 v32, v66, v67
	v_cvt_pk_bf16_f32 v33, v68, v69
	v_pk_mul_f32 v[70:71], v[48:49], v[70:71] op_sel_hi:[0,1]
	v_pk_mul_f32 v[72:73], v[48:49], v[72:73] op_sel_hi:[0,1]
	v_pk_mul_f32 v[70:71], v[104:105], v[70:71]
	v_pk_mul_f32 v[72:73], v[106:107], v[72:73]
	v_cvt_pk_bf16_f32 v34, v70, v71
	v_cvt_pk_bf16_f32 v35, v72, v73
	v_pk_mul_f32 v[74:75], v[48:49], v[74:75] op_sel_hi:[0,1]
	v_pk_mul_f32 v[76:77], v[48:49], v[76:77] op_sel_hi:[0,1]
	v_pk_mul_f32 v[74:75], v[108:109], v[74:75]
	v_pk_mul_f32 v[76:77], v[110:111], v[76:77]
	v_cvt_pk_bf16_f32 v36, v74, v75
	v_cvt_pk_bf16_f32 v37, v76, v77
	v_pk_mul_f32 v[78:79], v[48:49], v[78:79] op_sel_hi:[0,1]
	v_pk_mul_f32 v[80:81], v[48:49], v[80:81] op_sel_hi:[0,1]
	v_pk_mul_f32 v[78:79], v[112:113], v[78:79]
	v_pk_mul_f32 v[80:81], v[114:115], v[80:81]
	v_cvt_pk_bf16_f32 v38, v78, v79
	v_cvt_pk_bf16_f32 v39, v80, v81
	v_pk_mul_f32 v[82:83], v[50:51], v[82:83] op_sel_hi:[0,1]
	v_pk_mul_f32 v[84:85], v[50:51], v[84:85] op_sel_hi:[0,1]
	v_pk_mul_f32 v[82:83], v[100:101], v[82:83]
	v_pk_mul_f32 v[84:85], v[102:103], v[84:85]
	v_cvt_pk_bf16_f32 v40, v82, v83
	v_cvt_pk_bf16_f32 v41, v84, v85
	v_pk_mul_f32 v[86:87], v[50:51], v[86:87] op_sel_hi:[0,1]
	v_pk_mul_f32 v[88:89], v[50:51], v[88:89] op_sel_hi:[0,1]
	v_pk_mul_f32 v[86:87], v[104:105], v[86:87]
	v_pk_mul_f32 v[88:89], v[106:107], v[88:89]
	v_cvt_pk_bf16_f32 v42, v86, v87
	v_cvt_pk_bf16_f32 v43, v88, v89
	v_pk_mul_f32 v[90:91], v[50:51], v[90:91] op_sel_hi:[0,1]
	v_pk_mul_f32 v[92:93], v[50:51], v[92:93] op_sel_hi:[0,1]
	v_pk_mul_f32 v[90:91], v[108:109], v[90:91]
	v_pk_mul_f32 v[92:93], v[110:111], v[92:93]
	v_cvt_pk_bf16_f32 v44, v90, v91
	v_cvt_pk_bf16_f32 v45, v92, v93
	v_pk_mul_f32 v[94:95], v[50:51], v[94:95] op_sel_hi:[0,1]
	v_pk_mul_f32 v[96:97], v[50:51], v[96:97] op_sel_hi:[0,1]
	v_pk_mul_f32 v[94:95], v[112:113], v[94:95]
	v_pk_mul_f32 v[96:97], v[114:115], v[96:97]
	v_cvt_pk_bf16_f32 v46, v94, v95
	v_cvt_pk_bf16_f32 v47, v96, v97
	s_add_u32 s12, s4, 0x3000000
	s_addc_u32 s13, s5, 0
	s_add_u32 s14, s4, 0x3800000
	s_addc_u32 s15, s5, 0
	global_load_dwordx4 v[66:69], v116, s[12:13] nt
	global_load_dwordx4 v[70:73], v116, s[12:13] offset:1024 nt
	global_load_dwordx4 v[74:77], v116, s[12:13] offset:2048 nt
	global_load_dwordx4 v[78:81], v116, s[12:13] offset:3072 nt
	global_load_dwordx4 v[82:85], v116, s[14:15] nt
	global_load_dwordx4 v[86:89], v116, s[14:15] offset:1024 nt
	global_load_dwordx4 v[90:93], v116, s[14:15] offset:2048 nt
	global_load_dwordx4 v[94:97], v116, s[14:15] offset:3072 nt
	s_add_u32 s16, s20, 0x800000
	s_addc_u32 s17, s21, 0
	s_add_u32 s18, s20, 0xc00000
	s_addc_u32 s19, s21, 0
	global_store_dwordx2 v117, v[32:33], s[16:17]
	global_store_dwordx2 v117, v[34:35], s[16:17] offset:512
	global_store_dwordx2 v117, v[36:37], s[16:17] offset:1024
	global_store_dwordx2 v117, v[38:39], s[16:17] offset:1536
	global_store_dwordx2 v117, v[40:41], s[18:19]
	global_store_dwordx2 v117, v[42:43], s[18:19] offset:512
	global_store_dwordx2 v117, v[44:45], s[18:19] offset:1024
	global_store_dwordx2 v117, v[46:47], s[18:19] offset:1536
	s_waitcnt vmcnt(24)
	v_pk_mul_f32 v[48:49], v[0:1], v[0:1]
	v_pk_mul_f32 v[50:51], v[16:17], v[16:17]
	v_pk_fma_f32 v[48:49], v[2:3], v[2:3], v[48:49]
	v_pk_fma_f32 v[50:51], v[18:19], v[18:19], v[50:51]
	v_pk_fma_f32 v[48:49], v[4:5], v[4:5], v[48:49]
	v_pk_fma_f32 v[50:51], v[20:21], v[20:21], v[50:51]
	v_pk_fma_f32 v[48:49], v[6:7], v[6:7], v[48:49]
	v_pk_fma_f32 v[50:51], v[22:23], v[22:23], v[50:51]
	v_pk_fma_f32 v[48:49], v[8:9], v[8:9], v[48:49]
	v_pk_fma_f32 v[50:51], v[24:25], v[24:25], v[50:51]
	v_pk_fma_f32 v[48:49], v[10:11], v[10:11], v[48:49]
	v_pk_fma_f32 v[50:51], v[26:27], v[26:27], v[50:51]
	v_pk_fma_f32 v[48:49], v[12:13], v[12:13], v[48:49]
	v_pk_fma_f32 v[50:51], v[28:29], v[28:29], v[50:51]
	v_pk_fma_f32 v[48:49], v[14:15], v[14:15], v[48:49]
	v_pk_fma_f32 v[50:51], v[30:31], v[30:31], v[50:51]
	v_add_f32_e32 v48, v48, v49
	v_add_f32_e32 v50, v50, v51
	ds_bpermute_b32 v49, v58, v48
	ds_bpermute_b32 v51, v58, v50
	s_waitcnt lgkmcnt(0)
	v_add_f32_e32 v48, v48, v49
	v_add_f32_e32 v50, v50, v51
	ds_bpermute_b32 v49, v59, v48
	ds_bpermute_b32 v51, v59, v50
	s_waitcnt lgkmcnt(0)
	v_add_f32_e32 v48, v48, v49
	v_add_f32_e32 v50, v50, v51
	ds_bpermute_b32 v49, v60, v48
	ds_bpermute_b32 v51, v60, v50
	s_waitcnt lgkmcnt(0)
	v_add_f32_e32 v48, v48, v49
	v_add_f32_e32 v50, v50, v51
	ds_bpermute_b32 v49, v61, v48
	ds_bpermute_b32 v51, v61, v50
	s_waitcnt lgkmcnt(0)
	v_add_f32_e32 v48, v48, v49
	v_add_f32_e32 v50, v50, v51
	ds_bpermute_b32 v49, v62, v48
	ds_bpermute_b32 v51, v62, v50
	s_waitcnt lgkmcnt(0)
	v_add_f32_e32 v48, v48, v49
	v_add_f32_e32 v50, v50, v51
	ds_bpermute_b32 v49, v63, v48
	ds_bpermute_b32 v51, v63, v50
	s_waitcnt lgkmcnt(0)
	v_add_f32_e32 v48, v48, v49
	v_add_f32_e32 v50, v50, v51
	v_fmamk_f32 v48, v48, 0x3a800000, v64
	v_fmamk_f32 v50, v50, 0x3a800000, v64
	v_rsq_f32_e32 v48, v48
	v_rsq_f32_e32 v50, v50
	s_nop 0
	v_pk_mul_f32 v[0:1], v[48:49], v[0:1] op_sel_hi:[0,1]
	v_pk_mul_f32 v[2:3], v[48:49], v[2:3] op_sel_hi:[0,1]
	v_pk_mul_f32 v[0:1], v[100:101], v[0:1]
	v_pk_mul_f32 v[2:3], v[102:103], v[2:3]
	v_cvt_pk_bf16_f32 v32, v0, v1
	v_cvt_pk_bf16_f32 v33, v2, v3
	v_pk_mul_f32 v[4:5], v[48:49], v[4:5] op_sel_hi:[0,1]
	v_pk_mul_f32 v[6:7], v[48:49], v[6:7] op_sel_hi:[0,1]
	v_pk_mul_f32 v[4:5], v[104:105], v[4:5]
	v_pk_mul_f32 v[6:7], v[106:107], v[6:7]
	v_cvt_pk_bf16_f32 v34, v4, v5
	v_cvt_pk_bf16_f32 v35, v6, v7
	v_pk_mul_f32 v[8:9], v[48:49], v[8:9] op_sel_hi:[0,1]
	v_pk_mul_f32 v[10:11], v[48:49], v[10:11] op_sel_hi:[0,1]
	v_pk_mul_f32 v[8:9], v[108:109], v[8:9]
	v_pk_mul_f32 v[10:11], v[110:111], v[10:11]
	v_cvt_pk_bf16_f32 v36, v8, v9
	v_cvt_pk_bf16_f32 v37, v10, v11
	v_pk_mul_f32 v[12:13], v[48:49], v[12:13] op_sel_hi:[0,1]
	v_pk_mul_f32 v[14:15], v[48:49], v[14:15] op_sel_hi:[0,1]
	v_pk_mul_f32 v[12:13], v[112:113], v[12:13]
	v_pk_mul_f32 v[14:15], v[114:115], v[14:15]
	v_cvt_pk_bf16_f32 v38, v12, v13
	v_cvt_pk_bf16_f32 v39, v14, v15
	v_pk_mul_f32 v[16:17], v[50:51], v[16:17] op_sel_hi:[0,1]
	v_pk_mul_f32 v[18:19], v[50:51], v[18:19] op_sel_hi:[0,1]
	v_pk_mul_f32 v[16:17], v[100:101], v[16:17]
	v_pk_mul_f32 v[18:19], v[102:103], v[18:19]
	v_cvt_pk_bf16_f32 v40, v16, v17
	v_cvt_pk_bf16_f32 v41, v18, v19
	v_pk_mul_f32 v[20:21], v[50:51], v[20:21] op_sel_hi:[0,1]
	v_pk_mul_f32 v[22:23], v[50:51], v[22:23] op_sel_hi:[0,1]
	v_pk_mul_f32 v[20:21], v[104:105], v[20:21]
	v_pk_mul_f32 v[22:23], v[106:107], v[22:23]
	v_cvt_pk_bf16_f32 v42, v20, v21
	v_cvt_pk_bf16_f32 v43, v22, v23
	v_pk_mul_f32 v[24:25], v[50:51], v[24:25] op_sel_hi:[0,1]
	v_pk_mul_f32 v[26:27], v[50:51], v[26:27] op_sel_hi:[0,1]
	v_pk_mul_f32 v[24:25], v[108:109], v[24:25]
	v_pk_mul_f32 v[26:27], v[110:111], v[26:27]
	v_cvt_pk_bf16_f32 v44, v24, v25
	v_cvt_pk_bf16_f32 v45, v26, v27
	v_pk_mul_f32 v[28:29], v[50:51], v[28:29] op_sel_hi:[0,1]
	v_pk_mul_f32 v[30:31], v[50:51], v[30:31] op_sel_hi:[0,1]
	v_pk_mul_f32 v[28:29], v[112:113], v[28:29]
	v_pk_mul_f32 v[30:31], v[114:115], v[30:31]
	v_cvt_pk_bf16_f32 v46, v28, v29
	v_cvt_pk_bf16_f32 v47, v30, v31
	s_add_u32 s12, s4, 0x4000000
	s_addc_u32 s13, s5, 0
	s_add_u32 s14, s4, 0x4800000
	s_addc_u32 s15, s5, 0
	global_load_dwordx4 v[0:3], v116, s[12:13] nt
	global_load_dwordx4 v[4:7], v116, s[12:13] offset:1024 nt
	global_load_dwordx4 v[8:11], v116, s[12:13] offset:2048 nt
	global_load_dwordx4 v[12:15], v116, s[12:13] offset:3072 nt
	global_load_dwordx4 v[16:19], v116, s[14:15] nt
	global_load_dwordx4 v[20:23], v116, s[14:15] offset:1024 nt
	global_load_dwordx4 v[24:27], v116, s[14:15] offset:2048 nt
	global_load_dwordx4 v[28:31], v116, s[14:15] offset:3072 nt
	s_add_u32 s16, s20, 0x1000000
	s_addc_u32 s17, s21, 0
	s_add_u32 s18, s20, 0x1400000
	s_addc_u32 s19, s21, 0
	global_store_dwordx2 v117, v[32:33], s[16:17]
	global_store_dwordx2 v117, v[34:35], s[16:17] offset:512
	global_store_dwordx2 v117, v[36:37], s[16:17] offset:1024
	global_store_dwordx2 v117, v[38:39], s[16:17] offset:1536
	global_store_dwordx2 v117, v[40:41], s[18:19]
	global_store_dwordx2 v117, v[42:43], s[18:19] offset:512
	global_store_dwordx2 v117, v[44:45], s[18:19] offset:1024
	global_store_dwordx2 v117, v[46:47], s[18:19] offset:1536
	s_waitcnt vmcnt(24)
	v_pk_mul_f32 v[48:49], v[66:67], v[66:67]
	v_pk_mul_f32 v[50:51], v[82:83], v[82:83]
	v_pk_fma_f32 v[48:49], v[68:69], v[68:69], v[48:49]
	v_pk_fma_f32 v[50:51], v[84:85], v[84:85], v[50:51]
	v_pk_fma_f32 v[48:49], v[70:71], v[70:71], v[48:49]
	v_pk_fma_f32 v[50:51], v[86:87], v[86:87], v[50:51]
	v_pk_fma_f32 v[48:49], v[72:73], v[72:73], v[48:49]
	v_pk_fma_f32 v[50:51], v[88:89], v[88:89], v[50:51]
	v_pk_fma_f32 v[48:49], v[74:75], v[74:75], v[48:49]
	v_pk_fma_f32 v[50:51], v[90:91], v[90:91], v[50:51]
	v_pk_fma_f32 v[48:49], v[76:77], v[76:77], v[48:49]
	v_pk_fma_f32 v[50:51], v[92:93], v[92:93], v[50:51]
	v_pk_fma_f32 v[48:49], v[78:79], v[78:79], v[48:49]
	v_pk_fma_f32 v[50:51], v[94:95], v[94:95], v[50:51]
	v_pk_fma_f32 v[48:49], v[80:81], v[80:81], v[48:49]
	v_pk_fma_f32 v[50:51], v[96:97], v[96:97], v[50:51]
	v_add_f32_e32 v48, v48, v49
	v_add_f32_e32 v50, v50, v51
	ds_bpermute_b32 v49, v58, v48
	ds_bpermute_b32 v51, v58, v50
	s_waitcnt lgkmcnt(0)
	v_add_f32_e32 v48, v48, v49
	v_add_f32_e32 v50, v50, v51
	ds_bpermute_b32 v49, v59, v48
	ds_bpermute_b32 v51, v59, v50
	s_waitcnt lgkmcnt(0)
	v_add_f32_e32 v48, v48, v49
	v_add_f32_e32 v50, v50, v51
	ds_bpermute_b32 v49, v60, v48
	ds_bpermute_b32 v51, v60, v50
	s_waitcnt lgkmcnt(0)
	v_add_f32_e32 v48, v48, v49
	v_add_f32_e32 v50, v50, v51
	ds_bpermute_b32 v49, v61, v48
	ds_bpermute_b32 v51, v61, v50
	s_waitcnt lgkmcnt(0)
	v_add_f32_e32 v48, v48, v49
	v_add_f32_e32 v50, v50, v51
	ds_bpermute_b32 v49, v62, v48
	ds_bpermute_b32 v51, v62, v50
	s_waitcnt lgkmcnt(0)
	v_add_f32_e32 v48, v48, v49
	v_add_f32_e32 v50, v50, v51
	ds_bpermute_b32 v49, v63, v48
	ds_bpermute_b32 v51, v63, v50
	s_waitcnt lgkmcnt(0)
	v_add_f32_e32 v48, v48, v49
	v_add_f32_e32 v50, v50, v51
	v_fmamk_f32 v48, v48, 0x3a800000, v64
	v_fmamk_f32 v50, v50, 0x3a800000, v64
	v_rsq_f32_e32 v48, v48
	v_rsq_f32_e32 v50, v50
	s_nop 0
	v_pk_mul_f32 v[66:67], v[48:49], v[66:67] op_sel_hi:[0,1]
	v_pk_mul_f32 v[68:69], v[48:49], v[68:69] op_sel_hi:[0,1]
	v_pk_mul_f32 v[66:67], v[100:101], v[66:67]
	v_pk_mul_f32 v[68:69], v[102:103], v[68:69]
	v_cvt_pk_bf16_f32 v32, v66, v67
	v_cvt_pk_bf16_f32 v33, v68, v69
	v_pk_mul_f32 v[70:71], v[48:49], v[70:71] op_sel_hi:[0,1]
	v_pk_mul_f32 v[72:73], v[48:49], v[72:73] op_sel_hi:[0,1]
	v_pk_mul_f32 v[70:71], v[104:105], v[70:71]
	v_pk_mul_f32 v[72:73], v[106:107], v[72:73]
	v_cvt_pk_bf16_f32 v34, v70, v71
	v_cvt_pk_bf16_f32 v35, v72, v73
	v_pk_mul_f32 v[74:75], v[48:49], v[74:75] op_sel_hi:[0,1]
	v_pk_mul_f32 v[76:77], v[48:49], v[76:77] op_sel_hi:[0,1]
	v_pk_mul_f32 v[74:75], v[108:109], v[74:75]
	v_pk_mul_f32 v[76:77], v[110:111], v[76:77]
	v_cvt_pk_bf16_f32 v36, v74, v75
	v_cvt_pk_bf16_f32 v37, v76, v77
	v_pk_mul_f32 v[78:79], v[48:49], v[78:79] op_sel_hi:[0,1]
	v_pk_mul_f32 v[80:81], v[48:49], v[80:81] op_sel_hi:[0,1]
	v_pk_mul_f32 v[78:79], v[112:113], v[78:79]
	v_pk_mul_f32 v[80:81], v[114:115], v[80:81]
	v_cvt_pk_bf16_f32 v38, v78, v79
	v_cvt_pk_bf16_f32 v39, v80, v81
	v_pk_mul_f32 v[82:83], v[50:51], v[82:83] op_sel_hi:[0,1]
	v_pk_mul_f32 v[84:85], v[50:51], v[84:85] op_sel_hi:[0,1]
	v_pk_mul_f32 v[82:83], v[100:101], v[82:83]
	v_pk_mul_f32 v[84:85], v[102:103], v[84:85]
	v_cvt_pk_bf16_f32 v40, v82, v83
	v_cvt_pk_bf16_f32 v41, v84, v85
	v_pk_mul_f32 v[86:87], v[50:51], v[86:87] op_sel_hi:[0,1]
	v_pk_mul_f32 v[88:89], v[50:51], v[88:89] op_sel_hi:[0,1]
	v_pk_mul_f32 v[86:87], v[104:105], v[86:87]
	v_pk_mul_f32 v[88:89], v[106:107], v[88:89]
	v_cvt_pk_bf16_f32 v42, v86, v87
	v_cvt_pk_bf16_f32 v43, v88, v89
	v_pk_mul_f32 v[90:91], v[50:51], v[90:91] op_sel_hi:[0,1]
	v_pk_mul_f32 v[92:93], v[50:51], v[92:93] op_sel_hi:[0,1]
	v_pk_mul_f32 v[90:91], v[108:109], v[90:91]
	v_pk_mul_f32 v[92:93], v[110:111], v[92:93]
	v_cvt_pk_bf16_f32 v44, v90, v91
	v_cvt_pk_bf16_f32 v45, v92, v93
	v_pk_mul_f32 v[94:95], v[50:51], v[94:95] op_sel_hi:[0,1]
	v_pk_mul_f32 v[96:97], v[50:51], v[96:97] op_sel_hi:[0,1]
	v_pk_mul_f32 v[94:95], v[112:113], v[94:95]
	v_pk_mul_f32 v[96:97], v[114:115], v[96:97]
	v_cvt_pk_bf16_f32 v46, v94, v95
	v_cvt_pk_bf16_f32 v47, v96, v97
	s_add_u32 s12, s4, 0x5000000
	s_addc_u32 s13, s5, 0
	s_add_u32 s14, s4, 0x5800000
	s_addc_u32 s15, s5, 0
	global_load_dwordx4 v[66:69], v116, s[12:13] nt
	global_load_dwordx4 v[70:73], v116, s[12:13] offset:1024 nt
	global_load_dwordx4 v[74:77], v116, s[12:13] offset:2048 nt
	global_load_dwordx4 v[78:81], v116, s[12:13] offset:3072 nt
	global_load_dwordx4 v[82:85], v116, s[14:15] nt
	global_load_dwordx4 v[86:89], v116, s[14:15] offset:1024 nt
	global_load_dwordx4 v[90:93], v116, s[14:15] offset:2048 nt
	global_load_dwordx4 v[94:97], v116, s[14:15] offset:3072 nt
	s_add_u32 s16, s20, 0x1800000
	s_addc_u32 s17, s21, 0
	s_add_u32 s18, s20, 0x1c00000
	s_addc_u32 s19, s21, 0
	global_store_dwordx2 v117, v[32:33], s[16:17]
	global_store_dwordx2 v117, v[34:35], s[16:17] offset:512
	global_store_dwordx2 v117, v[36:37], s[16:17] offset:1024
	global_store_dwordx2 v117, v[38:39], s[16:17] offset:1536
	global_store_dwordx2 v117, v[40:41], s[18:19]
	global_store_dwordx2 v117, v[42:43], s[18:19] offset:512
	global_store_dwordx2 v117, v[44:45], s[18:19] offset:1024
	global_store_dwordx2 v117, v[46:47], s[18:19] offset:1536
	s_waitcnt vmcnt(24)
	v_pk_mul_f32 v[48:49], v[0:1], v[0:1]
	v_pk_mul_f32 v[50:51], v[16:17], v[16:17]
	v_pk_fma_f32 v[48:49], v[2:3], v[2:3], v[48:49]
	v_pk_fma_f32 v[50:51], v[18:19], v[18:19], v[50:51]
	v_pk_fma_f32 v[48:49], v[4:5], v[4:5], v[48:49]
	v_pk_fma_f32 v[50:51], v[20:21], v[20:21], v[50:51]
	v_pk_fma_f32 v[48:49], v[6:7], v[6:7], v[48:49]
	v_pk_fma_f32 v[50:51], v[22:23], v[22:23], v[50:51]
	v_pk_fma_f32 v[48:49], v[8:9], v[8:9], v[48:49]
	v_pk_fma_f32 v[50:51], v[24:25], v[24:25], v[50:51]
	v_pk_fma_f32 v[48:49], v[10:11], v[10:11], v[48:49]
	v_pk_fma_f32 v[50:51], v[26:27], v[26:27], v[50:51]
	v_pk_fma_f32 v[48:49], v[12:13], v[12:13], v[48:49]
	v_pk_fma_f32 v[50:51], v[28:29], v[28:29], v[50:51]
	v_pk_fma_f32 v[48:49], v[14:15], v[14:15], v[48:49]
	v_pk_fma_f32 v[50:51], v[30:31], v[30:31], v[50:51]
	v_add_f32_e32 v48, v48, v49
	v_add_f32_e32 v50, v50, v51
	ds_bpermute_b32 v49, v58, v48
	ds_bpermute_b32 v51, v58, v50
	s_waitcnt lgkmcnt(0)
	v_add_f32_e32 v48, v48, v49
	v_add_f32_e32 v50, v50, v51
	ds_bpermute_b32 v49, v59, v48
	ds_bpermute_b32 v51, v59, v50
	s_waitcnt lgkmcnt(0)
	v_add_f32_e32 v48, v48, v49
	v_add_f32_e32 v50, v50, v51
	ds_bpermute_b32 v49, v60, v48
	ds_bpermute_b32 v51, v60, v50
	s_waitcnt lgkmcnt(0)
	v_add_f32_e32 v48, v48, v49
	v_add_f32_e32 v50, v50, v51
	ds_bpermute_b32 v49, v61, v48
	ds_bpermute_b32 v51, v61, v50
	s_waitcnt lgkmcnt(0)
	v_add_f32_e32 v48, v48, v49
	v_add_f32_e32 v50, v50, v51
	ds_bpermute_b32 v49, v62, v48
	ds_bpermute_b32 v51, v62, v50
	s_waitcnt lgkmcnt(0)
	v_add_f32_e32 v48, v48, v49
	v_add_f32_e32 v50, v50, v51
	ds_bpermute_b32 v49, v63, v48
	ds_bpermute_b32 v51, v63, v50
	s_waitcnt lgkmcnt(0)
	v_add_f32_e32 v48, v48, v49
	v_add_f32_e32 v50, v50, v51
	v_fmamk_f32 v48, v48, 0x3a800000, v64
	v_fmamk_f32 v50, v50, 0x3a800000, v64
	v_rsq_f32_e32 v48, v48
	v_rsq_f32_e32 v50, v50
	s_nop 0
	v_pk_mul_f32 v[0:1], v[48:49], v[0:1] op_sel_hi:[0,1]
	v_pk_mul_f32 v[2:3], v[48:49], v[2:3] op_sel_hi:[0,1]
	v_pk_mul_f32 v[0:1], v[100:101], v[0:1]
	v_pk_mul_f32 v[2:3], v[102:103], v[2:3]
	v_cvt_pk_bf16_f32 v32, v0, v1
	v_cvt_pk_bf16_f32 v33, v2, v3
	v_pk_mul_f32 v[4:5], v[48:49], v[4:5] op_sel_hi:[0,1]
	v_pk_mul_f32 v[6:7], v[48:49], v[6:7] op_sel_hi:[0,1]
	v_pk_mul_f32 v[4:5], v[104:105], v[4:5]
	v_pk_mul_f32 v[6:7], v[106:107], v[6:7]
	v_cvt_pk_bf16_f32 v34, v4, v5
	v_cvt_pk_bf16_f32 v35, v6, v7
	v_pk_mul_f32 v[8:9], v[48:49], v[8:9] op_sel_hi:[0,1]
	v_pk_mul_f32 v[10:11], v[48:49], v[10:11] op_sel_hi:[0,1]
	v_pk_mul_f32 v[8:9], v[108:109], v[8:9]
	v_pk_mul_f32 v[10:11], v[110:111], v[10:11]
	v_cvt_pk_bf16_f32 v36, v8, v9
	v_cvt_pk_bf16_f32 v37, v10, v11
	v_pk_mul_f32 v[12:13], v[48:49], v[12:13] op_sel_hi:[0,1]
	v_pk_mul_f32 v[14:15], v[48:49], v[14:15] op_sel_hi:[0,1]
	v_pk_mul_f32 v[12:13], v[112:113], v[12:13]
	v_pk_mul_f32 v[14:15], v[114:115], v[14:15]
	v_cvt_pk_bf16_f32 v38, v12, v13
	v_cvt_pk_bf16_f32 v39, v14, v15
	v_pk_mul_f32 v[16:17], v[50:51], v[16:17] op_sel_hi:[0,1]
	v_pk_mul_f32 v[18:19], v[50:51], v[18:19] op_sel_hi:[0,1]
	v_pk_mul_f32 v[16:17], v[100:101], v[16:17]
	v_pk_mul_f32 v[18:19], v[102:103], v[18:19]
	v_cvt_pk_bf16_f32 v40, v16, v17
	v_cvt_pk_bf16_f32 v41, v18, v19
	v_pk_mul_f32 v[20:21], v[50:51], v[20:21] op_sel_hi:[0,1]
	v_pk_mul_f32 v[22:23], v[50:51], v[22:23] op_sel_hi:[0,1]
	v_pk_mul_f32 v[20:21], v[104:105], v[20:21]
	v_pk_mul_f32 v[22:23], v[106:107], v[22:23]
	v_cvt_pk_bf16_f32 v42, v20, v21
	v_cvt_pk_bf16_f32 v43, v22, v23
	v_pk_mul_f32 v[24:25], v[50:51], v[24:25] op_sel_hi:[0,1]
	v_pk_mul_f32 v[26:27], v[50:51], v[26:27] op_sel_hi:[0,1]
	v_pk_mul_f32 v[24:25], v[108:109], v[24:25]
	v_pk_mul_f32 v[26:27], v[110:111], v[26:27]
	v_cvt_pk_bf16_f32 v44, v24, v25
	v_cvt_pk_bf16_f32 v45, v26, v27
	v_pk_mul_f32 v[28:29], v[50:51], v[28:29] op_sel_hi:[0,1]
	v_pk_mul_f32 v[30:31], v[50:51], v[30:31] op_sel_hi:[0,1]
	v_pk_mul_f32 v[28:29], v[112:113], v[28:29]
	v_pk_mul_f32 v[30:31], v[114:115], v[30:31]
	v_cvt_pk_bf16_f32 v46, v28, v29
	v_cvt_pk_bf16_f32 v47, v30, v31
	s_add_u32 s12, s4, 0x6000000
	s_addc_u32 s13, s5, 0
	s_add_u32 s14, s4, 0x6800000
	s_addc_u32 s15, s5, 0
	global_load_dwordx4 v[0:3], v116, s[12:13] nt
	global_load_dwordx4 v[4:7], v116, s[12:13] offset:1024 nt
	global_load_dwordx4 v[8:11], v116, s[12:13] offset:2048 nt
	global_load_dwordx4 v[12:15], v116, s[12:13] offset:3072 nt
	global_load_dwordx4 v[16:19], v116, s[14:15] nt
	global_load_dwordx4 v[20:23], v116, s[14:15] offset:1024 nt
	global_load_dwordx4 v[24:27], v116, s[14:15] offset:2048 nt
	global_load_dwordx4 v[28:31], v116, s[14:15] offset:3072 nt
	s_add_u32 s16, s20, 0x2000000
	s_addc_u32 s17, s21, 0
	s_add_u32 s18, s20, 0x2400000
	s_addc_u32 s19, s21, 0
	global_store_dwordx2 v117, v[32:33], s[16:17]
	global_store_dwordx2 v117, v[34:35], s[16:17] offset:512
	global_store_dwordx2 v117, v[36:37], s[16:17] offset:1024
	global_store_dwordx2 v117, v[38:39], s[16:17] offset:1536
	global_store_dwordx2 v117, v[40:41], s[18:19]
	global_store_dwordx2 v117, v[42:43], s[18:19] offset:512
	global_store_dwordx2 v117, v[44:45], s[18:19] offset:1024
	global_store_dwordx2 v117, v[46:47], s[18:19] offset:1536
	s_waitcnt vmcnt(24)
	v_pk_mul_f32 v[48:49], v[66:67], v[66:67]
	v_pk_mul_f32 v[50:51], v[82:83], v[82:83]
	v_pk_fma_f32 v[48:49], v[68:69], v[68:69], v[48:49]
	v_pk_fma_f32 v[50:51], v[84:85], v[84:85], v[50:51]
	v_pk_fma_f32 v[48:49], v[70:71], v[70:71], v[48:49]
	v_pk_fma_f32 v[50:51], v[86:87], v[86:87], v[50:51]
	v_pk_fma_f32 v[48:49], v[72:73], v[72:73], v[48:49]
	v_pk_fma_f32 v[50:51], v[88:89], v[88:89], v[50:51]
	v_pk_fma_f32 v[48:49], v[74:75], v[74:75], v[48:49]
	v_pk_fma_f32 v[50:51], v[90:91], v[90:91], v[50:51]
	v_pk_fma_f32 v[48:49], v[76:77], v[76:77], v[48:49]
	v_pk_fma_f32 v[50:51], v[92:93], v[92:93], v[50:51]
	v_pk_fma_f32 v[48:49], v[78:79], v[78:79], v[48:49]
	v_pk_fma_f32 v[50:51], v[94:95], v[94:95], v[50:51]
	v_pk_fma_f32 v[48:49], v[80:81], v[80:81], v[48:49]
	v_pk_fma_f32 v[50:51], v[96:97], v[96:97], v[50:51]
	v_add_f32_e32 v48, v48, v49
	v_add_f32_e32 v50, v50, v51
	ds_bpermute_b32 v49, v58, v48
	ds_bpermute_b32 v51, v58, v50
	s_waitcnt lgkmcnt(0)
	v_add_f32_e32 v48, v48, v49
	v_add_f32_e32 v50, v50, v51
	ds_bpermute_b32 v49, v59, v48
	ds_bpermute_b32 v51, v59, v50
	s_waitcnt lgkmcnt(0)
	v_add_f32_e32 v48, v48, v49
	v_add_f32_e32 v50, v50, v51
	ds_bpermute_b32 v49, v60, v48
	ds_bpermute_b32 v51, v60, v50
	s_waitcnt lgkmcnt(0)
	v_add_f32_e32 v48, v48, v49
	v_add_f32_e32 v50, v50, v51
	ds_bpermute_b32 v49, v61, v48
	ds_bpermute_b32 v51, v61, v50
	s_waitcnt lgkmcnt(0)
	v_add_f32_e32 v48, v48, v49
	v_add_f32_e32 v50, v50, v51
	ds_bpermute_b32 v49, v62, v48
	ds_bpermute_b32 v51, v62, v50
	s_waitcnt lgkmcnt(0)
	v_add_f32_e32 v48, v48, v49
	v_add_f32_e32 v50, v50, v51
	ds_bpermute_b32 v49, v63, v48
	ds_bpermute_b32 v51, v63, v50
	s_waitcnt lgkmcnt(0)
	v_add_f32_e32 v48, v48, v49
	v_add_f32_e32 v50, v50, v51
	v_fmamk_f32 v48, v48, 0x3a800000, v64
	v_fmamk_f32 v50, v50, 0x3a800000, v64
	v_rsq_f32_e32 v48, v48
	v_rsq_f32_e32 v50, v50
	s_nop 0
	v_pk_mul_f32 v[66:67], v[48:49], v[66:67] op_sel_hi:[0,1]
	v_pk_mul_f32 v[68:69], v[48:49], v[68:69] op_sel_hi:[0,1]
	v_pk_mul_f32 v[66:67], v[100:101], v[66:67]
	v_pk_mul_f32 v[68:69], v[102:103], v[68:69]
	v_cvt_pk_bf16_f32 v32, v66, v67
	v_cvt_pk_bf16_f32 v33, v68, v69
	v_pk_mul_f32 v[70:71], v[48:49], v[70:71] op_sel_hi:[0,1]
	v_pk_mul_f32 v[72:73], v[48:49], v[72:73] op_sel_hi:[0,1]
	v_pk_mul_f32 v[70:71], v[104:105], v[70:71]
	v_pk_mul_f32 v[72:73], v[106:107], v[72:73]
	v_cvt_pk_bf16_f32 v34, v70, v71
	v_cvt_pk_bf16_f32 v35, v72, v73
	v_pk_mul_f32 v[74:75], v[48:49], v[74:75] op_sel_hi:[0,1]
	v_pk_mul_f32 v[76:77], v[48:49], v[76:77] op_sel_hi:[0,1]
	v_pk_mul_f32 v[74:75], v[108:109], v[74:75]
	v_pk_mul_f32 v[76:77], v[110:111], v[76:77]
	v_cvt_pk_bf16_f32 v36, v74, v75
	v_cvt_pk_bf16_f32 v37, v76, v77
	v_pk_mul_f32 v[78:79], v[48:49], v[78:79] op_sel_hi:[0,1]
	v_pk_mul_f32 v[80:81], v[48:49], v[80:81] op_sel_hi:[0,1]
	v_pk_mul_f32 v[78:79], v[112:113], v[78:79]
	v_pk_mul_f32 v[80:81], v[114:115], v[80:81]
	v_cvt_pk_bf16_f32 v38, v78, v79
	v_cvt_pk_bf16_f32 v39, v80, v81
	v_pk_mul_f32 v[82:83], v[50:51], v[82:83] op_sel_hi:[0,1]
	v_pk_mul_f32 v[84:85], v[50:51], v[84:85] op_sel_hi:[0,1]
	v_pk_mul_f32 v[82:83], v[100:101], v[82:83]
	v_pk_mul_f32 v[84:85], v[102:103], v[84:85]
	v_cvt_pk_bf16_f32 v40, v82, v83
	v_cvt_pk_bf16_f32 v41, v84, v85
	v_pk_mul_f32 v[86:87], v[50:51], v[86:87] op_sel_hi:[0,1]
	v_pk_mul_f32 v[88:89], v[50:51], v[88:89] op_sel_hi:[0,1]
	v_pk_mul_f32 v[86:87], v[104:105], v[86:87]
	v_pk_mul_f32 v[88:89], v[106:107], v[88:89]
	v_cvt_pk_bf16_f32 v42, v86, v87
	v_cvt_pk_bf16_f32 v43, v88, v89
	v_pk_mul_f32 v[90:91], v[50:51], v[90:91] op_sel_hi:[0,1]
	v_pk_mul_f32 v[92:93], v[50:51], v[92:93] op_sel_hi:[0,1]
	v_pk_mul_f32 v[90:91], v[108:109], v[90:91]
	v_pk_mul_f32 v[92:93], v[110:111], v[92:93]
	v_cvt_pk_bf16_f32 v44, v90, v91
	v_cvt_pk_bf16_f32 v45, v92, v93
	v_pk_mul_f32 v[94:95], v[50:51], v[94:95] op_sel_hi:[0,1]
	v_pk_mul_f32 v[96:97], v[50:51], v[96:97] op_sel_hi:[0,1]
	v_pk_mul_f32 v[94:95], v[112:113], v[94:95]
	v_pk_mul_f32 v[96:97], v[114:115], v[96:97]
	v_cvt_pk_bf16_f32 v46, v94, v95
	v_cvt_pk_bf16_f32 v47, v96, v97
	s_add_u32 s12, s4, 0x7000000
	s_addc_u32 s13, s5, 0
	s_add_u32 s14, s4, 0x7800000
	s_addc_u32 s15, s5, 0
	global_load_dwordx4 v[66:69], v116, s[12:13] nt
	global_load_dwordx4 v[70:73], v116, s[12:13] offset:1024 nt
	global_load_dwordx4 v[74:77], v116, s[12:13] offset:2048 nt
	global_load_dwordx4 v[78:81], v116, s[12:13] offset:3072 nt
	global_load_dwordx4 v[82:85], v116, s[14:15] nt
	global_load_dwordx4 v[86:89], v116, s[14:15] offset:1024 nt
	global_load_dwordx4 v[90:93], v116, s[14:15] offset:2048 nt
	global_load_dwordx4 v[94:97], v116, s[14:15] offset:3072 nt
	s_add_u32 s16, s20, 0x2800000
	s_addc_u32 s17, s21, 0
	s_add_u32 s18, s20, 0x2c00000
	s_addc_u32 s19, s21, 0
	global_store_dwordx2 v117, v[32:33], s[16:17]
	global_store_dwordx2 v117, v[34:35], s[16:17] offset:512
	global_store_dwordx2 v117, v[36:37], s[16:17] offset:1024
	global_store_dwordx2 v117, v[38:39], s[16:17] offset:1536
	global_store_dwordx2 v117, v[40:41], s[18:19]
	global_store_dwordx2 v117, v[42:43], s[18:19] offset:512
	global_store_dwordx2 v117, v[44:45], s[18:19] offset:1024
	global_store_dwordx2 v117, v[46:47], s[18:19] offset:1536
	s_waitcnt vmcnt(24)
	v_pk_mul_f32 v[48:49], v[0:1], v[0:1]
	v_pk_mul_f32 v[50:51], v[16:17], v[16:17]
	v_pk_fma_f32 v[48:49], v[2:3], v[2:3], v[48:49]
	v_pk_fma_f32 v[50:51], v[18:19], v[18:19], v[50:51]
	v_pk_fma_f32 v[48:49], v[4:5], v[4:5], v[48:49]
	v_pk_fma_f32 v[50:51], v[20:21], v[20:21], v[50:51]
	v_pk_fma_f32 v[48:49], v[6:7], v[6:7], v[48:49]
	v_pk_fma_f32 v[50:51], v[22:23], v[22:23], v[50:51]
	v_pk_fma_f32 v[48:49], v[8:9], v[8:9], v[48:49]
	v_pk_fma_f32 v[50:51], v[24:25], v[24:25], v[50:51]
	v_pk_fma_f32 v[48:49], v[10:11], v[10:11], v[48:49]
	v_pk_fma_f32 v[50:51], v[26:27], v[26:27], v[50:51]
	v_pk_fma_f32 v[48:49], v[12:13], v[12:13], v[48:49]
	v_pk_fma_f32 v[50:51], v[28:29], v[28:29], v[50:51]
	v_pk_fma_f32 v[48:49], v[14:15], v[14:15], v[48:49]
	v_pk_fma_f32 v[50:51], v[30:31], v[30:31], v[50:51]
	v_add_f32_e32 v48, v48, v49
	v_add_f32_e32 v50, v50, v51
	ds_bpermute_b32 v49, v58, v48
	ds_bpermute_b32 v51, v58, v50
	s_waitcnt lgkmcnt(0)
	v_add_f32_e32 v48, v48, v49
	v_add_f32_e32 v50, v50, v51
	ds_bpermute_b32 v49, v59, v48
	ds_bpermute_b32 v51, v59, v50
	s_waitcnt lgkmcnt(0)
	v_add_f32_e32 v48, v48, v49
	v_add_f32_e32 v50, v50, v51
	ds_bpermute_b32 v49, v60, v48
	ds_bpermute_b32 v51, v60, v50
	s_waitcnt lgkmcnt(0)
	v_add_f32_e32 v48, v48, v49
	v_add_f32_e32 v50, v50, v51
	ds_bpermute_b32 v49, v61, v48
	ds_bpermute_b32 v51, v61, v50
	s_waitcnt lgkmcnt(0)
	v_add_f32_e32 v48, v48, v49
	v_add_f32_e32 v50, v50, v51
	ds_bpermute_b32 v49, v62, v48
	ds_bpermute_b32 v51, v62, v50
	s_waitcnt lgkmcnt(0)
	v_add_f32_e32 v48, v48, v49
	v_add_f32_e32 v50, v50, v51
	ds_bpermute_b32 v49, v63, v48
	ds_bpermute_b32 v51, v63, v50
	s_waitcnt lgkmcnt(0)
	v_add_f32_e32 v48, v48, v49
	v_add_f32_e32 v50, v50, v51
	v_fmamk_f32 v48, v48, 0x3a800000, v64
	v_fmamk_f32 v50, v50, 0x3a800000, v64
	v_rsq_f32_e32 v48, v48
	v_rsq_f32_e32 v50, v50
	s_nop 0
	v_pk_mul_f32 v[0:1], v[48:49], v[0:1] op_sel_hi:[0,1]
	v_pk_mul_f32 v[2:3], v[48:49], v[2:3] op_sel_hi:[0,1]
	v_pk_mul_f32 v[0:1], v[100:101], v[0:1]
	v_pk_mul_f32 v[2:3], v[102:103], v[2:3]
	v_cvt_pk_bf16_f32 v32, v0, v1
	v_cvt_pk_bf16_f32 v33, v2, v3
	v_pk_mul_f32 v[4:5], v[48:49], v[4:5] op_sel_hi:[0,1]
	v_pk_mul_f32 v[6:7], v[48:49], v[6:7] op_sel_hi:[0,1]
	v_pk_mul_f32 v[4:5], v[104:105], v[4:5]
	v_pk_mul_f32 v[6:7], v[106:107], v[6:7]
	v_cvt_pk_bf16_f32 v34, v4, v5
	v_cvt_pk_bf16_f32 v35, v6, v7
	v_pk_mul_f32 v[8:9], v[48:49], v[8:9] op_sel_hi:[0,1]
	v_pk_mul_f32 v[10:11], v[48:49], v[10:11] op_sel_hi:[0,1]
	v_pk_mul_f32 v[8:9], v[108:109], v[8:9]
	v_pk_mul_f32 v[10:11], v[110:111], v[10:11]
	v_cvt_pk_bf16_f32 v36, v8, v9
	v_cvt_pk_bf16_f32 v37, v10, v11
	v_pk_mul_f32 v[12:13], v[48:49], v[12:13] op_sel_hi:[0,1]
	v_pk_mul_f32 v[14:15], v[48:49], v[14:15] op_sel_hi:[0,1]
	v_pk_mul_f32 v[12:13], v[112:113], v[12:13]
	v_pk_mul_f32 v[14:15], v[114:115], v[14:15]
	v_cvt_pk_bf16_f32 v38, v12, v13
	v_cvt_pk_bf16_f32 v39, v14, v15
	v_pk_mul_f32 v[16:17], v[50:51], v[16:17] op_sel_hi:[0,1]
	v_pk_mul_f32 v[18:19], v[50:51], v[18:19] op_sel_hi:[0,1]
	v_pk_mul_f32 v[16:17], v[100:101], v[16:17]
	v_pk_mul_f32 v[18:19], v[102:103], v[18:19]
	v_cvt_pk_bf16_f32 v40, v16, v17
	v_cvt_pk_bf16_f32 v41, v18, v19
	v_pk_mul_f32 v[20:21], v[50:51], v[20:21] op_sel_hi:[0,1]
	v_pk_mul_f32 v[22:23], v[50:51], v[22:23] op_sel_hi:[0,1]
	v_pk_mul_f32 v[20:21], v[104:105], v[20:21]
	v_pk_mul_f32 v[22:23], v[106:107], v[22:23]
	v_cvt_pk_bf16_f32 v42, v20, v21
	v_cvt_pk_bf16_f32 v43, v22, v23
	v_pk_mul_f32 v[24:25], v[50:51], v[24:25] op_sel_hi:[0,1]
	v_pk_mul_f32 v[26:27], v[50:51], v[26:27] op_sel_hi:[0,1]
	v_pk_mul_f32 v[24:25], v[108:109], v[24:25]
	v_pk_mul_f32 v[26:27], v[110:111], v[26:27]
	v_cvt_pk_bf16_f32 v44, v24, v25
	v_cvt_pk_bf16_f32 v45, v26, v27
	v_pk_mul_f32 v[28:29], v[50:51], v[28:29] op_sel_hi:[0,1]
	v_pk_mul_f32 v[30:31], v[50:51], v[30:31] op_sel_hi:[0,1]
	v_pk_mul_f32 v[28:29], v[112:113], v[28:29]
	v_pk_mul_f32 v[30:31], v[114:115], v[30:31]
	v_cvt_pk_bf16_f32 v46, v28, v29
	v_cvt_pk_bf16_f32 v47, v30, v31
	s_add_u32 s16, s20, 0x3000000
	s_addc_u32 s17, s21, 0
	s_add_u32 s18, s20, 0x3400000
	s_addc_u32 s19, s21, 0
	global_store_dwordx2 v117, v[32:33], s[16:17]
	global_store_dwordx2 v117, v[34:35], s[16:17] offset:512
	global_store_dwordx2 v117, v[36:37], s[16:17] offset:1024
	global_store_dwordx2 v117, v[38:39], s[16:17] offset:1536
	global_store_dwordx2 v117, v[40:41], s[18:19]
	global_store_dwordx2 v117, v[42:43], s[18:19] offset:512
	global_store_dwordx2 v117, v[44:45], s[18:19] offset:1024
	global_store_dwordx2 v117, v[46:47], s[18:19] offset:1536
	s_waitcnt vmcnt(16)
	v_pk_mul_f32 v[48:49], v[66:67], v[66:67]
	v_pk_mul_f32 v[50:51], v[82:83], v[82:83]
	v_pk_fma_f32 v[48:49], v[68:69], v[68:69], v[48:49]
	v_pk_fma_f32 v[50:51], v[84:85], v[84:85], v[50:51]
	v_pk_fma_f32 v[48:49], v[70:71], v[70:71], v[48:49]
	v_pk_fma_f32 v[50:51], v[86:87], v[86:87], v[50:51]
	v_pk_fma_f32 v[48:49], v[72:73], v[72:73], v[48:49]
	v_pk_fma_f32 v[50:51], v[88:89], v[88:89], v[50:51]
	v_pk_fma_f32 v[48:49], v[74:75], v[74:75], v[48:49]
	v_pk_fma_f32 v[50:51], v[90:91], v[90:91], v[50:51]
	v_pk_fma_f32 v[48:49], v[76:77], v[76:77], v[48:49]
	v_pk_fma_f32 v[50:51], v[92:93], v[92:93], v[50:51]
	v_pk_fma_f32 v[48:49], v[78:79], v[78:79], v[48:49]
	v_pk_fma_f32 v[50:51], v[94:95], v[94:95], v[50:51]
	v_pk_fma_f32 v[48:49], v[80:81], v[80:81], v[48:49]
	v_pk_fma_f32 v[50:51], v[96:97], v[96:97], v[50:51]
	v_add_f32_e32 v48, v48, v49
	v_add_f32_e32 v50, v50, v51
	ds_bpermute_b32 v49, v58, v48
	ds_bpermute_b32 v51, v58, v50
	s_waitcnt lgkmcnt(0)
	v_add_f32_e32 v48, v48, v49
	v_add_f32_e32 v50, v50, v51
	ds_bpermute_b32 v49, v59, v48
	ds_bpermute_b32 v51, v59, v50
	s_waitcnt lgkmcnt(0)
	v_add_f32_e32 v48, v48, v49
	v_add_f32_e32 v50, v50, v51
	ds_bpermute_b32 v49, v60, v48
	ds_bpermute_b32 v51, v60, v50
	s_waitcnt lgkmcnt(0)
	v_add_f32_e32 v48, v48, v49
	v_add_f32_e32 v50, v50, v51
	ds_bpermute_b32 v49, v61, v48
	ds_bpermute_b32 v51, v61, v50
	s_waitcnt lgkmcnt(0)
	v_add_f32_e32 v48, v48, v49
	v_add_f32_e32 v50, v50, v51
	ds_bpermute_b32 v49, v62, v48
	ds_bpermute_b32 v51, v62, v50
	s_waitcnt lgkmcnt(0)
	v_add_f32_e32 v48, v48, v49
	v_add_f32_e32 v50, v50, v51
	ds_bpermute_b32 v49, v63, v48
	ds_bpermute_b32 v51, v63, v50
	s_waitcnt lgkmcnt(0)
	v_add_f32_e32 v48, v48, v49
	v_add_f32_e32 v50, v50, v51
	v_fmamk_f32 v48, v48, 0x3a800000, v64
	v_fmamk_f32 v50, v50, 0x3a800000, v64
	v_rsq_f32_e32 v48, v48
	v_rsq_f32_e32 v50, v50
	s_nop 0
	v_pk_mul_f32 v[66:67], v[48:49], v[66:67] op_sel_hi:[0,1]
	v_pk_mul_f32 v[68:69], v[48:49], v[68:69] op_sel_hi:[0,1]
	v_pk_mul_f32 v[66:67], v[100:101], v[66:67]
	v_pk_mul_f32 v[68:69], v[102:103], v[68:69]
	v_cvt_pk_bf16_f32 v32, v66, v67
	v_cvt_pk_bf16_f32 v33, v68, v69
	v_pk_mul_f32 v[70:71], v[48:49], v[70:71] op_sel_hi:[0,1]
	v_pk_mul_f32 v[72:73], v[48:49], v[72:73] op_sel_hi:[0,1]
	v_pk_mul_f32 v[70:71], v[104:105], v[70:71]
	v_pk_mul_f32 v[72:73], v[106:107], v[72:73]
	v_cvt_pk_bf16_f32 v34, v70, v71
	v_cvt_pk_bf16_f32 v35, v72, v73
	v_pk_mul_f32 v[74:75], v[48:49], v[74:75] op_sel_hi:[0,1]
	v_pk_mul_f32 v[76:77], v[48:49], v[76:77] op_sel_hi:[0,1]
	v_pk_mul_f32 v[74:75], v[108:109], v[74:75]
	v_pk_mul_f32 v[76:77], v[110:111], v[76:77]
	v_cvt_pk_bf16_f32 v36, v74, v75
	v_cvt_pk_bf16_f32 v37, v76, v77
	v_pk_mul_f32 v[78:79], v[48:49], v[78:79] op_sel_hi:[0,1]
	v_pk_mul_f32 v[80:81], v[48:49], v[80:81] op_sel_hi:[0,1]
	v_pk_mul_f32 v[78:79], v[112:113], v[78:79]
	v_pk_mul_f32 v[80:81], v[114:115], v[80:81]
	v_cvt_pk_bf16_f32 v38, v78, v79
	v_cvt_pk_bf16_f32 v39, v80, v81
	v_pk_mul_f32 v[82:83], v[50:51], v[82:83] op_sel_hi:[0,1]
	v_pk_mul_f32 v[84:85], v[50:51], v[84:85] op_sel_hi:[0,1]
	v_pk_mul_f32 v[82:83], v[100:101], v[82:83]
	v_pk_mul_f32 v[84:85], v[102:103], v[84:85]
	v_cvt_pk_bf16_f32 v40, v82, v83
	v_cvt_pk_bf16_f32 v41, v84, v85
	v_pk_mul_f32 v[86:87], v[50:51], v[86:87] op_sel_hi:[0,1]
	v_pk_mul_f32 v[88:89], v[50:51], v[88:89] op_sel_hi:[0,1]
	v_pk_mul_f32 v[86:87], v[104:105], v[86:87]
	v_pk_mul_f32 v[88:89], v[106:107], v[88:89]
	v_cvt_pk_bf16_f32 v42, v86, v87
	v_cvt_pk_bf16_f32 v43, v88, v89
	v_pk_mul_f32 v[90:91], v[50:51], v[90:91] op_sel_hi:[0,1]
	v_pk_mul_f32 v[92:93], v[50:51], v[92:93] op_sel_hi:[0,1]
	v_pk_mul_f32 v[90:91], v[108:109], v[90:91]
	v_pk_mul_f32 v[92:93], v[110:111], v[92:93]
	v_cvt_pk_bf16_f32 v44, v90, v91
	v_cvt_pk_bf16_f32 v45, v92, v93
	v_pk_mul_f32 v[94:95], v[50:51], v[94:95] op_sel_hi:[0,1]
	v_pk_mul_f32 v[96:97], v[50:51], v[96:97] op_sel_hi:[0,1]
	v_pk_mul_f32 v[94:95], v[112:113], v[94:95]
	v_pk_mul_f32 v[96:97], v[114:115], v[96:97]
	v_cvt_pk_bf16_f32 v46, v94, v95
	v_cvt_pk_bf16_f32 v47, v96, v97
	s_add_u32 s16, s20, 0x3800000
	s_addc_u32 s17, s21, 0
	s_add_u32 s18, s20, 0x3c00000
	s_addc_u32 s19, s21, 0
	global_store_dwordx2 v117, v[32:33], s[16:17]
	global_store_dwordx2 v117, v[34:35], s[16:17] offset:512
	global_store_dwordx2 v117, v[36:37], s[16:17] offset:1024
	global_store_dwordx2 v117, v[38:39], s[16:17] offset:1536
	global_store_dwordx2 v117, v[40:41], s[18:19]
	global_store_dwordx2 v117, v[42:43], s[18:19] offset:512
	global_store_dwordx2 v117, v[44:45], s[18:19] offset:1024
	global_store_dwordx2 v117, v[46:47], s[18:19] offset:1536
	s_branch .LBB0_265

.LBB0_674:
	v_readlane_b32 s98, v148, 0
	v_readlane_b32 s99, v149, 0
	v_readlane_b32 s0, v148, 4
	v_readlane_b32 s1, v149, 4
	s_nop 0
	s_or_b64 s[98:99], s[98:99], s[0:1]
	v_readlane_b32 s0, v148, 8
	v_readlane_b32 s1, v149, 8
	s_nop 0
	s_or_b64 s[98:99], s[98:99], s[0:1]
	v_readlane_b32 s0, v148, 12
	v_readlane_b32 s1, v149, 12
	s_nop 0
	s_or_b64 s[98:99], s[98:99], s[0:1]
	v_readlane_b32 s0, v148, 16
	v_readlane_b32 s1, v149, 16
	s_nop 0
	s_or_b64 s[98:99], s[98:99], s[0:1]
	v_readlane_b32 s0, v148, 20
	v_readlane_b32 s1, v149, 20
	s_nop 0
	s_or_b64 s[98:99], s[98:99], s[0:1]
	v_readlane_b32 s0, v148, 24
	v_readlane_b32 s1, v149, 24
	s_nop 0
	s_or_b64 s[98:99], s[98:99], s[0:1]
	v_readlane_b32 s0, v148, 28
	v_readlane_b32 s1, v149, 28
	s_nop 0
	s_or_b64 s[98:99], s[98:99], s[0:1]
	s_flbit_i32_b64 s0, s[4:5]
	s_xor_b32 s8, s0, 63
	s_lshl_b64 s[0:1], 1, s8
	s_andn2_b64 s[0:1], s[4:5], s[0:1]
	v_mad_u64_u32 v[2:3], s[10:11], v116, s34, v[108:109]
	s_flbit_i32_b64 s6, s[0:1]
	v_lshlrev_b32_e32 v3, 1, v2
	s_xor_b32 s6, s6, 63
	v_add_u32_e32 v133, 0, v3
	v_lshlrev_b32_e32 v3, 2, v116
	s_cmp_lg_u64 s[0:1], 0
	v_sub_u32_e32 v2, v2, v3
	s_cselect_b32 s77, s6, -1
	v_lshl_add_u32 v2, v2, 1, 0
	v_lshlrev_b64 v[122:123], 12, v[116:117]
	v_add_u32_e32 v126, 0x11200, v133
	v_add_u32_e32 v127, 0x15a00, v2
	s_cmp_lt_i32 s77, 0
	s_waitcnt vmcnt(1)
	ds_write_b128 v126, v[98:101]
	s_waitcnt vmcnt(0)
	ds_write2_b64 v127, v[102:103], v[104:105] offset1:1
	s_cbranch_scc1 .LBB0_676
	v_lshl_add_u32 v4, s77, 6, v116
	v_mov_b64_e32 v[2:3], s[2:3]
	v_mad_i64_i32 v[2:3], s[10:11], v4, s85, v[2:3]
	v_lshlrev_b64 v[4:5], 13, v[116:117]
	v_lshl_add_u64 v[4:5], s[94:95], 0, v[4:5]
	s_lshl_b32 s82, s77, 7
	v_lshl_add_u64 v[2:3], v[2:3], 0, v[0:1]
	v_lshl_add_u64 v[4:5], v[4:5], 0, s[82:83]
	v_lshl_add_u64 v[4:5], v[4:5], 0, v[0:1]
	global_load_dwordx4 v[110:113], v[2:3], off offset:512
	global_load_dwordx4 v[106:109], v[4:5], off
	s_branch .LBB0_677

.LBB0_688:
	s_bitcmp1_b64 s[98:99], s73
	s_cbranch_scc0 .Lsel_skip1
	v_add_u32_e32 v132, 0x11200, v174
	ds_read_b128 v[50:53], v132
	ds_read_b128 v[142:145], v132 offset:32
	ds_read_b128 v[150:153], v132 offset:4608
	ds_read_b128 v[170:173], v132 offset:4640
	ds_read_b128 v[176:179], v132 offset:64
	ds_read_b128 v[180:183], v132 offset:96
	ds_read_b128 v[184:187], v132 offset:4672
	ds_read_b128 v[188:191], v132 offset:4704
	s_waitcnt lgkmcnt(7)
	v_mfma_f32_32x32x16_bf16 v[66:81], v[50:53], v[82:85], v[34:49]
	s_cmp_lg_u32 s73, s79
	s_waitcnt lgkmcnt(5)
	v_mfma_f32_32x32x16_bf16 v[50:65], v[150:153], v[82:85], v[34:49]
	v_mfma_f32_32x32x16_bf16 v[66:81], v[142:145], v[86:89], v[66:81]
	s_waitcnt lgkmcnt(4)
	v_mfma_f32_32x32x16_bf16 v[50:65], v[170:173], v[86:89], v[50:65]
	s_waitcnt lgkmcnt(3)
	v_mfma_f32_32x32x16_bf16 v[66:81], v[176:179], v[90:93], v[66:81]
	s_waitcnt lgkmcnt(1)
	v_mfma_f32_32x32x16_bf16 v[50:65], v[184:187], v[90:93], v[50:65]
	v_mfma_f32_32x32x16_bf16 v[66:81], v[180:183], v[94:97], v[66:81]
	s_waitcnt lgkmcnt(0)
	v_mfma_f32_32x32x16_bf16 v[50:65], v[188:191], v[94:97], v[50:65]
	s_cbranch_scc1 .LBB0_690
	s_nop 8
	v_cndmask_b32_e64 v66, v66, v158, s[70:71]
	s_nop 0
	v_cndmask_b32_e64 v50, v50, v158, s[4:5]
	v_cndmask_b32_e64 v67, v67, v158, s[6:7]
	v_cndmask_b32_e64 v51, v51, v158, s[8:9]
	v_cndmask_b32_e64 v68, v68, v158, s[10:11]
	v_cndmask_b32_e64 v52, v52, v158, s[12:13]
	v_cndmask_b32_e64 v69, v69, v158, s[14:15]
	v_cndmask_b32_e64 v53, v53, v158, s[16:17]
	v_cndmask_b32_e64 v70, v70, v158, s[18:19]
	v_cndmask_b32_e64 v54, v54, v158, s[20:21]
	v_cndmask_b32_e64 v71, v71, v158, s[22:23]
	v_cndmask_b32_e64 v55, v55, v158, s[24:25]
	v_cndmask_b32_e64 v72, v72, v158, s[26:27]
	v_cndmask_b32_e64 v56, v56, v158, s[28:29]
	v_cndmask_b32_e64 v73, v73, v158, s[30:31]
	v_cndmask_b32_e64 v57, v57, v158, s[34:35]
	v_cndmask_b32_e64 v74, v74, v158, s[36:37]
	v_cndmask_b32_e64 v58, v58, v158, s[38:39]
	v_cndmask_b32_e64 v75, v75, v158, s[40:41]
	v_cndmask_b32_e64 v59, v59, v158, s[42:43]
	v_cndmask_b32_e64 v76, v76, v158, s[44:45]
	v_cndmask_b32_e64 v60, v60, v158, s[46:47]
	v_cndmask_b32_e64 v77, v77, v158, s[48:49]
	v_cndmask_b32_e64 v61, v61, v158, s[50:51]
	v_cndmask_b32_e64 v78, v78, v158, s[52:53]
	v_cndmask_b32_e64 v62, v62, v158, s[54:55]
	v_cndmask_b32_e64 v79, v79, v158, s[56:57]
	v_cndmask_b32_e64 v63, v63, v158, s[58:59]
	v_cndmask_b32_e64 v80, v80, v158, s[60:61]
	v_cndmask_b32_e64 v64, v64, v158, s[62:63]
	v_cndmask_b32_e64 v81, v81, v158, s[64:65]
	v_cndmask_b32_e64 v65, v65, v158, s[66:67]

.Lsel_skip1:
	s_waitcnt lgkmcnt(0)

.LBB0_700:
	s_bitcmp1_b64 s[98:99], s77
	s_cbranch_scc0 .Lsel_skip2
	v_add_u32_e32 v54, 0x13600, v174
	ds_read_b128 v[50:53], v54
	ds_read_b128 v[142:145], v54 offset:32
	ds_read_b128 v[150:153], v54 offset:4608
	ds_read_b128 v[170:173], v54 offset:4640
	ds_read_b128 v[176:179], v54 offset:64
	ds_read_b128 v[180:183], v54 offset:96
	ds_read_b128 v[184:187], v54 offset:4672
	ds_read_b128 v[188:191], v54 offset:4704
	s_waitcnt lgkmcnt(7)
	v_mfma_f32_32x32x16_bf16 v[66:81], v[50:53], v[82:85], v[34:49]
	s_cmp_lg_u32 s77, s79
	s_waitcnt lgkmcnt(5)
	v_mfma_f32_32x32x16_bf16 v[50:65], v[150:153], v[82:85], v[34:49]
	v_mfma_f32_32x32x16_bf16 v[66:81], v[142:145], v[86:89], v[66:81]
	s_waitcnt lgkmcnt(4)
	v_mfma_f32_32x32x16_bf16 v[50:65], v[170:173], v[86:89], v[50:65]
	s_waitcnt lgkmcnt(3)
	v_mfma_f32_32x32x16_bf16 v[66:81], v[176:179], v[90:93], v[66:81]
	s_waitcnt lgkmcnt(1)
	v_mfma_f32_32x32x16_bf16 v[50:65], v[184:187], v[90:93], v[50:65]
	v_mfma_f32_32x32x16_bf16 v[66:81], v[180:183], v[94:97], v[66:81]
	s_waitcnt lgkmcnt(0)
	v_mfma_f32_32x32x16_bf16 v[50:65], v[188:191], v[94:97], v[50:65]
	s_cbranch_scc1 .LBB0_702
	s_nop 8
	v_cndmask_b32_e64 v66, v66, v158, s[70:71]
	s_nop 0
	v_cndmask_b32_e64 v50, v50, v158, s[4:5]
	v_cndmask_b32_e64 v67, v67, v158, s[6:7]
	v_cndmask_b32_e64 v51, v51, v158, s[8:9]
	v_cndmask_b32_e64 v68, v68, v158, s[10:11]
	v_cndmask_b32_e64 v52, v52, v158, s[12:13]
	v_cndmask_b32_e64 v69, v69, v158, s[14:15]
	v_cndmask_b32_e64 v53, v53, v158, s[16:17]
	v_cndmask_b32_e64 v70, v70, v158, s[18:19]
	v_cndmask_b32_e64 v54, v54, v158, s[20:21]
	v_cndmask_b32_e64 v71, v71, v158, s[22:23]
	v_cndmask_b32_e64 v55, v55, v158, s[24:25]
	v_cndmask_b32_e64 v72, v72, v158, s[26:27]
	v_cndmask_b32_e64 v56, v56, v158, s[28:29]
	v_cndmask_b32_e64 v73, v73, v158, s[30:31]
	v_cndmask_b32_e64 v57, v57, v158, s[34:35]
	v_cndmask_b32_e64 v74, v74, v158, s[36:37]
	v_cndmask_b32_e64 v58, v58, v158, s[38:39]
	v_cndmask_b32_e64 v75, v75, v158, s[40:41]
	v_cndmask_b32_e64 v59, v59, v158, s[42:43]
	v_cndmask_b32_e64 v76, v76, v158, s[44:45]
	v_cndmask_b32_e64 v60, v60, v158, s[46:47]
	v_cndmask_b32_e64 v77, v77, v158, s[48:49]
	v_cndmask_b32_e64 v61, v61, v158, s[50:51]
	v_cndmask_b32_e64 v78, v78, v158, s[52:53]
	v_cndmask_b32_e64 v62, v62, v158, s[54:55]
	v_cndmask_b32_e64 v79, v79, v158, s[56:57]
	v_cndmask_b32_e64 v63, v63, v158, s[58:59]
	v_cndmask_b32_e64 v80, v80, v158, s[60:61]
	v_cndmask_b32_e64 v64, v64, v158, s[62:63]
	v_cndmask_b32_e64 v81, v81, v158, s[64:65]
	v_cndmask_b32_e64 v65, v65, v158, s[66:67]

.LBB0_821:
	s_cmpk_lg_i32 s30, 0x400
	s_cbranch_scc1 .LBB0_820
	v_mov_b32_e32 v2, v184
	v_mov_b32_e32 v132, v186
	s_nop 0
	v_ashrrev_i32_e32 v3, 31, v2
	v_lshlrev_b64 v[2:3], 11, v[2:3]
	v_ashrrev_i32_e32 v133, 31, v132
	v_lshl_add_u64 v[2:3], s[76:77], 0, v[2:3]
	v_lshl_add_u64 v[2:3], v[132:133], 1, v[2:3]
	v_mov_b32_e32 v237, 0
	global_load_dwordx4 v[132:135], v[2:3], off
	global_load_dwordx4 v[136:139], v[2:3], off offset:256
	v_mov_b32_e32 v236, s48
	v_lshl_add_u64 v[232:233], v[2:3], 0, v[236:237]
	global_load_dwordx4 v[140:143], v[232:233], off
	v_lshl_add_u64 v[234:235], v[2:3], 0, s[12:13]
	global_load_dwordx4 v[144:147], v[234:235], off offset:256
	v_mov_b32_e32 v236, s44
	v_lshl_add_u64 v[232:233], v[2:3], 0, v[236:237]
	global_load_dwordx4 v[148:151], v[232:233], off
	v_lshl_add_u64 v[234:235], v[2:3], 0, s[14:15]
	global_load_dwordx4 v[152:155], v[234:235], off offset:256
	v_mov_b32_e32 v236, s47
	v_lshl_add_u64 v[232:233], v[2:3], 0, v[236:237]
	global_load_dwordx4 v[156:159], v[232:233], off
	v_lshl_add_u64 v[234:235], v[2:3], 0, s[16:17]
	global_load_dwordx4 v[160:163], v[234:235], off offset:256
	v_mov_b32_e32 v236, s51
	v_lshl_add_u64 v[232:233], v[2:3], 0, v[236:237]
	global_load_dwordx4 v[164:167], v[232:233], off
	v_lshl_add_u64 v[234:235], v[2:3], 0, s[18:19]
	global_load_dwordx4 v[204:207], v[234:235], off offset:256
	v_mov_b32_e32 v236, s52
	v_lshl_add_u64 v[232:233], v[2:3], 0, v[236:237]
	global_load_dwordx4 v[208:211], v[232:233], off
	v_lshl_add_u64 v[234:235], v[2:3], 0, s[20:21]
	global_load_dwordx4 v[212:215], v[234:235], off offset:256
	v_mov_b32_e32 v236, s53
	v_lshl_add_u64 v[232:233], v[2:3], 0, v[236:237]
	global_load_dwordx4 v[216:219], v[232:233], off
	v_lshl_add_u64 v[234:235], v[2:3], 0, s[22:23]
	global_load_dwordx4 v[220:223], v[234:235], off offset:256
	v_mov_b32_e32 v236, s54
	v_lshl_add_u64 v[232:233], v[2:3], 0, v[236:237]
	global_load_dwordx4 v[224:227], v[232:233], off
	v_lshl_add_u64 v[234:235], v[2:3], 0, s[24:25]
	global_load_dwordx4 v[228:231], v[234:235], off offset:256
	s_waitcnt vmcnt(0)
	v_lshlrev_b32_e32 v238, 16, v133
	v_and_b32_e32 v239, 0xffff0000, v133
	v_pk_mul_f32 v[130:131], v[130:131], v[238:239]
	v_lshlrev_b32_e32 v240, 16, v137
	v_and_b32_e32 v241, 0xffff0000, v137
	v_pk_mul_f32 v[118:119], v[118:119], v[240:241]
	v_lshlrev_b32_e32 v242, 16, v140
	v_and_b32_e32 v243, 0xffff0000, v140
	v_pk_mul_f32 v[120:121], v[120:121], v[242:243]
	v_lshlrev_b32_e32 v244, 16, v135
	v_and_b32_e32 v245, 0xffff0000, v135
	v_pk_mul_f32 v[126:127], v[126:127], v[244:245]
	v_lshlrev_b32_e32 v246, 16, v139
	v_and_b32_e32 v247, 0xffff0000, v139
	v_pk_mul_f32 v[114:115], v[114:115], v[246:247]
	v_lshlrev_b32_e32 v192, 16, v142
	v_and_b32_e32 v193, 0xffff0000, v142
	v_pk_mul_f32 v[108:109], v[108:109], v[192:193]
	v_lshlrev_b32_e32 v200, 16, v141
	v_and_b32_e32 v201, 0xffff0000, v141
	v_pk_mul_f32 v[122:123], v[122:123], v[200:201]
	v_lshlrev_b32_e32 v232, 16, v143
	v_and_b32_e32 v233, 0xffff0000, v143
	v_pk_mul_f32 v[110:111], v[110:111], v[232:233]
	v_lshlrev_b32_e32 v234, 16, v150
	v_and_b32_e32 v235, 0xffff0000, v150
	v_pk_mul_f32 v[92:93], v[92:93], v[234:235]
	v_lshlrev_b32_e32 v236, 16, v151
	v_and_b32_e32 v237, 0xffff0000, v151
	v_pk_mul_f32 v[94:95], v[94:95], v[236:237]
	v_lshlrev_b32_e32 v238, 16, v152
	v_and_b32_e32 v239, 0xffff0000, v152
	v_pk_mul_f32 v[88:89], v[88:89], v[238:239]
	v_lshlrev_b32_e32 v240, 16, v153
	v_and_b32_e32 v241, 0xffff0000, v153
	v_pk_mul_f32 v[90:91], v[90:91], v[240:241]
	v_lshlrev_b32_e32 v242, 16, v154
	v_and_b32_e32 v243, 0xffff0000, v154
	v_pk_mul_f32 v[84:85], v[84:85], v[242:243]
	v_lshlrev_b32_e32 v244, 16, v144
	v_and_b32_e32 v245, 0xffff0000, v144
	v_pk_mul_f32 v[104:105], v[104:105], v[244:245]
	v_lshlrev_b32_e32 v246, 16, v132
	v_and_b32_e32 v247, 0xffff0000, v132
	v_pk_mul_f32 v[128:129], v[128:129], v[246:247]
	v_lshlrev_b32_e32 v192, 16, v145
	v_and_b32_e32 v193, 0xffff0000, v145
	v_pk_mul_f32 v[106:107], v[106:107], v[192:193]
	v_lshlrev_b32_e32 v200, 16, v155
	v_and_b32_e32 v201, 0xffff0000, v155
	v_pk_mul_f32 v[86:87], v[86:87], v[200:201]
	v_lshlrev_b32_e32 v232, 16, v149
	v_and_b32_e32 v233, 0xffff0000, v149
	v_pk_mul_f32 v[98:99], v[98:99], v[232:233]
	v_lshlrev_b32_e32 v234, 16, v146
	v_and_b32_e32 v235, 0xffff0000, v146
	v_pk_mul_f32 v[100:101], v[100:101], v[234:235]
	v_lshlrev_b32_e32 v236, 16, v156
	v_and_b32_e32 v237, 0xffff0000, v156
	v_pk_mul_f32 v[80:81], v[80:81], v[236:237]
	v_lshlrev_b32_e32 v238, 16, v157
	v_and_b32_e32 v239, 0xffff0000, v157
	v_pk_mul_f32 v[82:83], v[82:83], v[238:239]
	v_lshlrev_b32_e32 v240, 16, v158
	v_and_b32_e32 v241, 0xffff0000, v158
	v_pk_mul_f32 v[76:77], v[76:77], v[240:241]
	v_lshlrev_b32_e32 v242, 16, v159
	v_and_b32_e32 v243, 0xffff0000, v159
	v_pk_mul_f32 v[78:79], v[78:79], v[242:243]
	v_lshlrev_b32_e32 v244, 16, v160
	v_and_b32_e32 v245, 0xffff0000, v160
	v_pk_mul_f32 v[72:73], v[72:73], v[244:245]
	v_lshlrev_b32_e32 v246, 16, v161
	v_and_b32_e32 v247, 0xffff0000, v161
	v_pk_mul_f32 v[74:75], v[74:75], v[246:247]
	v_lshlrev_b32_e32 v192, 16, v163
	v_and_b32_e32 v193, 0xffff0000, v163
	v_pk_mul_f32 v[70:71], v[70:71], v[192:193]
	v_lshlrev_b32_e32 v200, 16, v162
	v_and_b32_e32 v201, 0xffff0000, v162
	v_pk_mul_f32 v[68:69], v[68:69], v[200:201]
	v_lshlrev_b32_e32 v232, 16, v165
	v_and_b32_e32 v233, 0xffff0000, v165
	v_pk_mul_f32 v[66:67], v[66:67], v[232:233]
	v_lshlrev_b32_e32 v234, 16, v167
	v_and_b32_e32 v235, 0xffff0000, v167
	v_pk_mul_f32 v[62:63], v[62:63], v[234:235]
	v_lshlrev_b32_e32 v236, 16, v166
	v_and_b32_e32 v237, 0xffff0000, v166
	v_pk_mul_f32 v[60:61], v[60:61], v[236:237]
	v_lshlrev_b32_e32 v238, 16, v205
	v_and_b32_e32 v239, 0xffff0000, v205
	v_pk_mul_f32 v[58:59], v[58:59], v[238:239]
	v_lshlrev_b32_e32 v240, 16, v204
	v_and_b32_e32 v241, 0xffff0000, v204
	v_pk_mul_f32 v[56:57], v[56:57], v[240:241]
	v_lshlrev_b32_e32 v242, 16, v207
	v_and_b32_e32 v243, 0xffff0000, v207
	v_pk_mul_f32 v[54:55], v[54:55], v[242:243]
	v_lshlrev_b32_e32 v244, 16, v206
	v_and_b32_e32 v245, 0xffff0000, v206
	v_pk_mul_f32 v[52:53], v[52:53], v[244:245]
	v_lshlrev_b32_e32 v246, 16, v209
	v_and_b32_e32 v247, 0xffff0000, v209
	v_pk_mul_f32 v[50:51], v[50:51], v[246:247]
	v_lshlrev_b32_e32 v192, 16, v208
	v_and_b32_e32 v193, 0xffff0000, v208
	v_pk_mul_f32 v[48:49], v[48:49], v[192:193]
	v_lshlrev_b32_e32 v200, 16, v211
	v_and_b32_e32 v201, 0xffff0000, v211
	v_pk_mul_f32 v[46:47], v[46:47], v[200:201]
	v_lshlrev_b32_e32 v232, 16, v210
	v_and_b32_e32 v233, 0xffff0000, v210
	v_pk_mul_f32 v[44:45], v[44:45], v[232:233]
	v_lshlrev_b32_e32 v234, 16, v213
	v_and_b32_e32 v235, 0xffff0000, v213
	v_pk_mul_f32 v[42:43], v[42:43], v[234:235]
	v_lshlrev_b32_e32 v236, 16, v212
	v_and_b32_e32 v237, 0xffff0000, v212
	v_pk_mul_f32 v[40:41], v[40:41], v[236:237]
	v_lshlrev_b32_e32 v238, 16, v215
	v_and_b32_e32 v239, 0xffff0000, v215
	v_pk_mul_f32 v[38:39], v[38:39], v[238:239]
	v_lshlrev_b32_e32 v240, 16, v214
	v_and_b32_e32 v241, 0xffff0000, v214
	v_pk_mul_f32 v[36:37], v[36:37], v[240:241]
	v_lshlrev_b32_e32 v242, 16, v217
	v_and_b32_e32 v243, 0xffff0000, v217
	v_pk_mul_f32 v[34:35], v[34:35], v[242:243]
	v_lshlrev_b32_e32 v244, 16, v216
	v_and_b32_e32 v245, 0xffff0000, v216
	v_pk_mul_f32 v[32:33], v[32:33], v[244:245]
	v_lshlrev_b32_e32 v246, 16, v219
	v_and_b32_e32 v247, 0xffff0000, v219
	v_pk_mul_f32 v[30:31], v[30:31], v[246:247]
	v_lshlrev_b32_e32 v192, 16, v218
	v_and_b32_e32 v193, 0xffff0000, v218
	v_pk_mul_f32 v[28:29], v[28:29], v[192:193]
	v_lshlrev_b32_e32 v200, 16, v134
	v_and_b32_e32 v201, 0xffff0000, v134
	v_pk_mul_f32 v[124:125], v[124:125], v[200:201]
	v_lshlrev_b32_e32 v232, 16, v221
	v_and_b32_e32 v233, 0xffff0000, v221
	v_pk_mul_f32 v[26:27], v[26:27], v[232:233]
	v_lshlrev_b32_e32 v234, 16, v220
	v_and_b32_e32 v235, 0xffff0000, v220
	v_pk_mul_f32 v[24:25], v[24:25], v[234:235]
	v_lshlrev_b32_e32 v236, 16, v223
	v_and_b32_e32 v237, 0xffff0000, v223
	v_pk_mul_f32 v[22:23], v[22:23], v[236:237]
	v_lshlrev_b32_e32 v238, 16, v222
	v_and_b32_e32 v239, 0xffff0000, v222
	v_pk_mul_f32 v[20:21], v[20:21], v[238:239]
	v_lshlrev_b32_e32 v240, 16, v225
	v_and_b32_e32 v241, 0xffff0000, v225
	v_pk_mul_f32 v[18:19], v[18:19], v[240:241]
	v_lshlrev_b32_e32 v242, 16, v224
	v_and_b32_e32 v243, 0xffff0000, v224
	v_pk_mul_f32 v[16:17], v[16:17], v[242:243]
	v_lshlrev_b32_e32 v244, 16, v227
	v_and_b32_e32 v245, 0xffff0000, v227
	v_pk_mul_f32 v[14:15], v[14:15], v[244:245]
	v_lshlrev_b32_e32 v246, 16, v226
	v_and_b32_e32 v247, 0xffff0000, v226
	v_pk_mul_f32 v[12:13], v[12:13], v[246:247]
	v_lshlrev_b32_e32 v192, 16, v229
	v_and_b32_e32 v193, 0xffff0000, v229
	v_pk_mul_f32 v[10:11], v[10:11], v[192:193]
	v_lshlrev_b32_e32 v200, 16, v228
	v_and_b32_e32 v201, 0xffff0000, v228
	v_pk_mul_f32 v[8:9], v[8:9], v[200:201]
	v_lshlrev_b32_e32 v232, 16, v136
	v_and_b32_e32 v233, 0xffff0000, v136
	v_pk_mul_f32 v[116:117], v[116:117], v[232:233]
	v_lshlrev_b32_e32 v234, 16, v138
	v_and_b32_e32 v235, 0xffff0000, v138
	v_pk_mul_f32 v[112:113], v[112:113], v[234:235]
	v_lshlrev_b32_e32 v236, 16, v147
	v_and_b32_e32 v237, 0xffff0000, v147
	v_pk_mul_f32 v[102:103], v[102:103], v[236:237]
	v_lshlrev_b32_e32 v238, 16, v148
	v_and_b32_e32 v239, 0xffff0000, v148
	v_pk_mul_f32 v[96:97], v[96:97], v[238:239]
	v_lshlrev_b32_e32 v240, 16, v164
	v_and_b32_e32 v241, 0xffff0000, v164
	v_pk_mul_f32 v[64:65], v[64:65], v[240:241]
	v_lshlrev_b32_e32 v242, 16, v231
	v_and_b32_e32 v243, 0xffff0000, v231
	v_pk_mul_f32 v[6:7], v[6:7], v[242:243]
	v_lshlrev_b32_e32 v244, 16, v230
	v_and_b32_e32 v245, 0xffff0000, v230
	v_pk_mul_f32 v[4:5], v[4:5], v[244:245]
	s_branch .LBB0_820

	.amdhsa_kernel _Z13nsa_block_fwd4Args
		.amdhsa_group_segment_fixed_size 0
		.amdhsa_private_segment_fixed_size 0
		.amdhsa_kernarg_size 408
		.amdhsa_user_sgpr_count 2
		.amdhsa_user_sgpr_dispatch_ptr 0
		.amdhsa_user_sgpr_queue_ptr 0
		.amdhsa_user_sgpr_kernarg_segment_ptr 1
		.amdhsa_user_sgpr_dispatch_id 0
		.amdhsa_user_sgpr_kernarg_preload_length 0
		.amdhsa_user_sgpr_kernarg_preload_offset 0
		.amdhsa_user_sgpr_private_segment_size 0
		.amdhsa_uses_dynamic_stack 0
		.amdhsa_enable_private_segment 0
		.amdhsa_system_sgpr_workgroup_id_x 1
		.amdhsa_system_sgpr_workgroup_id_y 0
		.amdhsa_system_sgpr_workgroup_id_z 0
		.amdhsa_system_sgpr_workgroup_info 0
		.amdhsa_system_vgpr_workitem_id 2
		.amdhsa_next_free_vgpr 250
		.amdhsa_next_free_sgpr 100
		.amdhsa_accum_offset 252
		.amdhsa_reserve_vcc 1
		.amdhsa_float_round_mode_32 0
		.amdhsa_float_round_mode_16_64 0
		.amdhsa_float_denorm_mode_32 3
		.amdhsa_float_denorm_mode_16_64 3
		.amdhsa_dx10_clamp 1
		.amdhsa_ieee_mode 1
		.amdhsa_fp16_overflow 0
		.amdhsa_tg_split 0
		.amdhsa_exception_fp_ieee_invalid_op 0
		.amdhsa_exception_fp_denorm_src 0
		.amdhsa_exception_fp_ieee_div_zero 0
		.amdhsa_exception_fp_ieee_overflow 0
		.amdhsa_exception_fp_ieee_underflow 0
		.amdhsa_exception_fp_ieee_inexact 0
		.amdhsa_exception_int_div_zero 0
	.end_amdhsa_kernel

amdhsa.kernels:
  - .agpr_count:     0
    .args:
      - .offset:         0
        .size:           152
        .value_kind:     by_value
      - .offset:         152
        .size:           4
        .value_kind:     hidden_block_count_x
      - .offset:         156
        .size:           4
        .value_kind:     hidden_block_count_y
      - .offset:         160
        .size:           4
        .value_kind:     hidden_block_count_z
      - .offset:         164
        .size:           2
        .value_kind:     hidden_group_size_x
      - .offset:         166
        .size:           2
        .value_kind:     hidden_group_size_y
      - .offset:         168
        .size:           2
        .value_kind:     hidden_group_size_z
      - .offset:         170
        .size:           2
        .value_kind:     hidden_remainder_x
      - .offset:         172
        .size:           2
        .value_kind:     hidden_remainder_y
      - .offset:         174
        .size:           2
        .value_kind:     hidden_remainder_z
      - .offset:         192
        .size:           8
        .value_kind:     hidden_global_offset_x
      - .offset:         200
        .size:           8
        .value_kind:     hidden_global_offset_y
      - .offset:         208
        .size:           8
        .value_kind:     hidden_global_offset_z
      - .offset:         216
        .size:           2
        .value_kind:     hidden_grid_dims
      - .offset:         240
        .size:           8
        .value_kind:     hidden_multigrid_sync_arg
      - .offset:         272
        .size:           4
        .value_kind:     hidden_dynamic_lds_size
    .group_segment_fixed_size: 0
    .kernarg_segment_align: 8
    .kernarg_segment_size: 408
    .language:       OpenCL C
    .language_version:
      - 2
      - 0
    .max_flat_workgroup_size: 512
    .name:           _Z13nsa_block_fwd4Args
    .private_segment_fixed_size: 0
    .sgpr_count:     106
    .sgpr_spill_count: 74
    .symbol:         _Z13nsa_block_fwd4Args.kd
    .uniform_work_group_size: 1
    .uses_dynamic_stack: false
    .vgpr_count:     250
    .vgpr_spill_count: 0
    .wavefront_size: 64
